# DPP for the row max / row sum butterflies of the sample memory attention and for the 16-lane score reductions of the sample window attention
# baseline (speedup 1.0000x reference)
.LBB0_532:
	s_ashr_i32 s44, s40, 4
	s_add_i32 s20, s44, 0x4000
	s_and_b32 s41, s40, 15
	s_ashr_i32 s21, s20, 31
	s_mul_i32 s23, s20, 0x1800
	s_mul_hi_i32 s22, s20, 0x1800
	s_add_u32 s23, s0, s23
	s_addc_u32 s24, s1, s22
	s_lshl_b32 s22, s41, 7
	s_add_u32 s22, s23, s22
	s_addc_u32 s23, s24, 0
	s_lshl_b64 s[30:31], s[20:21], 8
	s_add_u32 s21, s4, s30
	s_addc_u32 s24, s9, s31
	s_lshl_b32 s42, s40, 3
	s_and_b32 s45, s42, 64
	s_lshl_b32 s46, s45, 1
	s_add_u32 s42, s21, s46
	s_addc_u32 s43, s24, 0
	s_add_u32 s21, s14, s30
	s_addc_u32 s24, s28, s31
	s_add_u32 s30, s21, s46
	s_waitcnt vmcnt(24) lgkmcnt(2)
	v_lshl_add_u64 v[6:7], s[42:43], 0, v[104:105]
	s_addc_u32 s31, s24, 0
	s_add_i32 s24, s41, s29
	v_lshl_add_u64 v[4:5], s[22:23], 0, v[104:105]
	global_load_dwordx2 v[6:7], v[6:7], off
	s_nop 0
	global_load_dwordx2 v[106:107], v2, s[30:31]
	global_load_dwordx2 v[112:113], v[4:5], off
	s_lshl_b64 s[30:31], s[24:25], 2
	s_add_u32 s30, s2, s30
	s_addc_u32 s31, s3, s31
	global_load_dword v120, v3, s[30:31] offset:-128
	v_lshl_or_b32 v4, s44, 7, v197
	v_ashrrev_i32_e32 v5, 31, v4
	v_lshlrev_b64 v[110:111], 9, v[4:5]
	v_lshl_or_b32 v110, s45, 2, v110
	v_lshl_add_u64 v[4:5], v[100:101], 0, v[110:111]
	s_waitcnt vmcnt(3)
	v_lshlrev_b32_e32 v121, 16, v6
	v_and_b32_e32 v123, 0xffff0000, v6
	v_lshlrev_b32_e32 v122, 16, v7
	v_and_b32_e32 v124, 0xffff0000, v7
	v_add_co_u32_e32 v6, vcc, s17, v4
	global_load_dwordx4 v[126:129], v[4:5], off
	global_load_dwordx4 v[130:133], v[4:5], off offset:2048
	v_addc_co_u32_e32 v7, vcc, 0, v5, vcc
	v_add_co_u32_e32 v108, vcc, s91, v4
	s_movk_i32 s21, 0x6000
	s_nop 0
	v_addc_co_u32_e32 v109, vcc, 0, v5, vcc
	v_add_co_u32_e32 v8, vcc, s50, v4
	global_load_dwordx4 v[134:137], v[108:109], off
	global_load_dwordx4 v[138:141], v[108:109], off offset:2048
	v_addc_co_u32_e32 v9, vcc, 0, v5, vcc
	s_waitcnt lgkmcnt(1)
	v_add_co_u32_e32 v10, vcc, s90, v4
	s_waitcnt vmcnt(4)
	v_mul_f32_e32 v120, 0x3fb8aa3b, v120
	s_waitcnt lgkmcnt(0)
	v_addc_co_u32_e32 v11, vcc, 0, v5, vcc
	global_load_dwordx4 v[142:145], v[6:7], off offset:2048
	global_load_dwordx4 v[146:149], v[8:9], off offset:2048
	global_load_dwordx4 v[150:153], v[10:11], off offset:-4096
	global_load_dwordx4 v[96:99], v[10:11], off
	v_add_co_u32_e32 v6, vcc, s96, v4
	s_nop 1
	v_addc_co_u32_e32 v7, vcc, 0, v5, vcc
	v_add_co_u32_e32 v8, vcc, s21, v4
	s_nop 1
	v_addc_co_u32_e32 v9, vcc, 0, v5, vcc
	global_load_dwordx4 v[92:95], v[10:11], off offset:2048
	global_load_dwordx4 v[88:91], v[8:9], off offset:-4096
	global_load_dwordx4 v[80:83], v[8:9], off
	global_load_dwordx4 v[76:79], v[8:9], off offset:2048
	v_add_co_u32_e32 v8, vcc, s51, v4
	s_nop 1
	v_addc_co_u32_e32 v9, vcc, 0, v5, vcc
	v_add_co_u32_e32 v10, vcc, s92, v4
	s_nop 1
	v_addc_co_u32_e32 v11, vcc, 0, v5, vcc
	global_load_dwordx4 v[84:87], v[6:7], off offset:2048
	global_load_dwordx4 v[68:71], v[8:9], off offset:2048
	global_load_dwordx4 v[72:75], v[10:11], off offset:-4096
	global_load_dwordx4 v[64:67], v[10:11], off
	v_add_co_u32_e32 v6, vcc, s56, v4
	s_nop 1
	v_addc_co_u32_e32 v7, vcc, 0, v5, vcc
	v_add_co_u32_e32 v8, vcc, s93, v4
	s_nop 1
	v_addc_co_u32_e32 v9, vcc, 0, v5, vcc
	global_load_dwordx4 v[60:63], v[10:11], off offset:2048
	global_load_dwordx4 v[56:59], v[8:9], off offset:-4096
	global_load_dwordx4 v[48:51], v[8:9], off
	global_load_dwordx4 v[44:47], v[8:9], off offset:2048
	v_add_co_u32_e32 v8, vcc, s57, v4
	s_nop 1
	v_addc_co_u32_e32 v9, vcc, 0, v5, vcc
	v_add_co_u32_e32 v10, vcc, s6, v4
	s_nop 1
	v_addc_co_u32_e32 v11, vcc, 0, v5, vcc
	global_load_dwordx4 v[52:55], v[6:7], off offset:2048
	global_load_dwordx4 v[36:39], v[8:9], off offset:2048
	global_load_dwordx4 v[40:43], v[10:11], off offset:-4096
	global_load_dwordx4 v[32:35], v[10:11], off
	v_add_co_u32_e32 v6, vcc, s58, v4
	s_nop 1
	v_addc_co_u32_e32 v7, vcc, 0, v5, vcc
	v_add_co_u32_e32 v8, vcc, s95, v4
	s_nop 1
	v_addc_co_u32_e32 v9, vcc, 0, v5, vcc
	v_add_co_u32_e32 v4, vcc, s52, v4
	global_load_dwordx4 v[28:31], v[10:11], off offset:2048
	global_load_dwordx4 v[24:27], v[8:9], off offset:-4096
	global_load_dwordx4 v[16:19], v[8:9], off
	global_load_dwordx4 v[12:15], v[8:9], off offset:2048
	v_addc_co_u32_e32 v5, vcc, 0, v5, vcc
	global_load_dwordx4 v[20:23], v[6:7], off offset:2048
	global_load_dwordx4 v[8:11], v[4:5], off
	global_load_dwordx4 v[154:157], v[108:109], off offset:-4096
	s_nop 0
	global_load_dwordx4 v[4:7], v[4:5], off offset:2048
	v_and_b32_e32 v108, 0xffff0000, v112
	v_lshlrev_b32_e32 v109, 16, v113
	v_lshlrev_b32_e32 v112, 16, v112
	v_and_b32_e32 v113, 0xffff0000, v113
	s_waitcnt vmcnt(31)
	v_mov_b32_e32 v158, v127
	v_mov_b32_e32 v127, v129
	v_mov_b32_e32 v159, v128
	v_pk_mul_f32 v[126:127], v[126:127], v[112:113]
	s_movk_i32 s33, 0x6000
	v_pk_fma_f32 v[126:127], v[158:159], v[108:109], v[126:127]
	s_nop 0
	v_add_f32_e32 v125, v126, v127
	s_waitcnt vmcnt(30)
	v_mov_b32_e32 v126, v131
	v_mov_b32_e32 v131, v133
	v_mov_b32_e32 v127, v132
	v_pk_mul_f32 v[128:129], v[130:131], v[112:113]
	s_nop 1
	v_mov_b32_dpp v158, v125 quad_perm:[1,0,3,2] row_mask:0xf bank_mask:0xf
	v_pk_fma_f32 v[126:127], v[126:127], v[108:109], v[128:129]
	s_waitcnt lgkmcnt(0)
	v_add_f32_e32 v125, v125, v158
	v_add_f32_e32 v126, v126, v127
	s_nop 1
	v_mov_b32_dpp v127, v126 quad_perm:[1,0,3,2] row_mask:0xf bank_mask:0xf
	s_nop 1
	v_mov_b32_dpp v128, v125 quad_perm:[2,3,0,1] row_mask:0xf bank_mask:0xf
	s_waitcnt lgkmcnt(0)
	v_add_f32_e32 v126, v126, v127
	s_nop 1
	v_mov_b32_dpp v127, v126 quad_perm:[2,3,0,1] row_mask:0xf bank_mask:0xf
	s_waitcnt lgkmcnt(0)
	v_add_f32_e32 v125, v125, v128
	s_nop 1
	v_mov_b32_dpp v128, v125 row_half_mirror row_mask:0xf bank_mask:0xf
	s_waitcnt lgkmcnt(0)
	v_add_f32_e32 v126, v126, v127
	s_nop 1
	v_mov_b32_dpp v127, v126 row_half_mirror row_mask:0xf bank_mask:0xf
	s_waitcnt lgkmcnt(0)
	v_add_f32_e32 v125, v125, v128
	s_nop 1
	v_mov_b32_dpp v130, v125 row_mirror row_mask:0xf bank_mask:0xf
	s_waitcnt lgkmcnt(0)
	v_add_f32_e32 v131, v126, v127
	s_waitcnt vmcnt(1)
	v_mov_b32_e32 v126, v155
	v_mov_b32_e32 v155, v157
	v_mov_b32_e32 v127, v156
	v_pk_mul_f32 v[128:129], v[154:155], v[112:113]
	s_nop 1
	v_mov_b32_dpp v132, v131 row_mirror row_mask:0xf bank_mask:0xf
	v_pk_fma_f32 v[126:127], v[126:127], v[108:109], v[128:129]
	s_waitcnt lgkmcnt(0)
	v_add_f32_e32 v130, v125, v130
	v_add_f32_e32 v133, v126, v127
	v_mov_b32_e32 v126, v143
	v_mov_b32_e32 v143, v145
	v_mov_b32_e32 v127, v144
	v_pk_mul_f32 v[128:129], v[142:143], v[112:113]
	s_nop 1
	v_mov_b32_dpp v154, v133 quad_perm:[1,0,3,2] row_mask:0xf bank_mask:0xf
	v_pk_fma_f32 v[126:127], v[126:127], v[108:109], v[128:129]
	v_mov_b32_e32 v129, v136
	v_add_f32_e32 v127, v126, v127
	s_nop 1
	v_mov_b32_dpp v128, v127 quad_perm:[1,0,3,2] row_mask:0xf bank_mask:0xf
	s_waitcnt lgkmcnt(0)
	v_add_f32_e32 v126, v131, v132
	s_waitcnt lgkmcnt(0)
	v_add_f32_e32 v125, v133, v154
	s_nop 1
	v_mov_b32_dpp v131, v125 quad_perm:[2,3,0,1] row_mask:0xf bank_mask:0xf
	s_waitcnt lgkmcnt(0)
	v_add_f32_e32 v127, v127, v128
	v_mov_b32_e32 v128, v135
	v_mov_b32_e32 v135, v137
	v_pk_mul_f32 v[132:133], v[134:135], v[112:113]
	s_nop 1
	v_mov_b32_dpp v142, v127 quad_perm:[2,3,0,1] row_mask:0xf bank_mask:0xf
	v_pk_fma_f32 v[128:129], v[128:129], v[108:109], v[132:133]
	s_waitcnt lgkmcnt(0)
	v_add_f32_e32 v125, v125, v131
	v_add_f32_e32 v128, v128, v129
	s_nop 1
	v_mov_b32_dpp v129, v128 quad_perm:[1,0,3,2] row_mask:0xf bank_mask:0xf
	s_waitcnt lgkmcnt(0)
	v_add_f32_e32 v127, v127, v142
	s_nop 1
	v_mov_b32_dpp v132, v127 row_half_mirror row_mask:0xf bank_mask:0xf
	s_nop 1
	v_mov_b32_dpp v131, v125 row_half_mirror row_mask:0xf bank_mask:0xf
	s_waitcnt lgkmcnt(0)
	v_add_f32_e32 v128, v128, v129
	s_nop 1
	v_mov_b32_dpp v129, v128 quad_perm:[2,3,0,1] row_mask:0xf bank_mask:0xf
	s_waitcnt lgkmcnt(0)
	v_add_f32_e32 v127, v127, v132
	s_waitcnt lgkmcnt(0)
	v_add_f32_e32 v125, v125, v131
	s_nop 1
	v_mov_b32_dpp v131, v125 row_mirror row_mask:0xf bank_mask:0xf
	s_nop 1
	v_mov_b32_dpp v134, v127 row_mirror row_mask:0xf bank_mask:0xf
	s_waitcnt lgkmcnt(0)
	v_add_f32_e32 v135, v128, v129
	v_mov_b32_e32 v128, v139
	v_mov_b32_e32 v139, v141
	v_mov_b32_e32 v129, v140
	v_pk_mul_f32 v[132:133], v[138:139], v[112:113]
	s_nop 1
	v_mov_b32_dpp v136, v135 row_half_mirror row_mask:0xf bank_mask:0xf
	v_pk_fma_f32 v[128:129], v[128:129], v[108:109], v[132:133]
	v_mov_b32_e32 v133, v152
	v_add_f32_e32 v129, v128, v129
	s_nop 1
	v_mov_b32_dpp v132, v129 quad_perm:[1,0,3,2] row_mask:0xf bank_mask:0xf
	s_waitcnt lgkmcnt(0)
	v_add_f32_e32 v128, v125, v131
	s_waitcnt lgkmcnt(0)
	v_add_f32_e32 v125, v127, v134
	s_waitcnt lgkmcnt(0)
	v_add_f32_e32 v127, v135, v136
	s_nop 1
	v_mov_b32_dpp v131, v127 row_mirror row_mask:0xf bank_mask:0xf
	s_waitcnt lgkmcnt(0)
	v_add_f32_e32 v129, v129, v132
	v_mov_b32_e32 v132, v151
	v_mov_b32_e32 v151, v153
	v_pk_mul_f32 v[134:135], v[150:151], v[112:113]
	s_nop 1
	v_mov_b32_dpp v136, v129 quad_perm:[2,3,0,1] row_mask:0xf bank_mask:0xf
	v_pk_fma_f32 v[132:133], v[132:133], v[108:109], v[134:135]
	s_waitcnt lgkmcnt(0)
	v_add_f32_e32 v129, v129, v136
	v_add_f32_e32 v137, v132, v133
	v_mov_b32_e32 v132, v147
	v_mov_b32_e32 v147, v149
	v_mov_b32_e32 v133, v148
	v_pk_mul_f32 v[134:135], v[146:147], v[112:113]
	s_nop 1
	v_mov_b32_dpp v138, v137 quad_perm:[1,0,3,2] row_mask:0xf bank_mask:0xf
	v_pk_fma_f32 v[132:133], v[132:133], v[108:109], v[134:135]
	s_nop 1
	v_mov_b32_dpp v134, v129 row_half_mirror row_mask:0xf bank_mask:0xf
	v_add_f32_e32 v132, v132, v133
	s_nop 1
	v_mov_b32_dpp v133, v132 quad_perm:[1,0,3,2] row_mask:0xf bank_mask:0xf
	s_waitcnt lgkmcnt(0)
	v_add_f32_e32 v135, v137, v138
	s_nop 1
	v_mov_b32_dpp v136, v135 quad_perm:[2,3,0,1] row_mask:0xf bank_mask:0xf
	s_waitcnt lgkmcnt(0)
	v_add_f32_e32 v134, v129, v134
	v_add_f32_e32 v129, v127, v131
	s_waitcnt lgkmcnt(0)
	v_add_f32_e32 v132, v132, v133
	s_nop 1
	v_mov_b32_dpp v133, v132 quad_perm:[2,3,0,1] row_mask:0xf bank_mask:0xf
	s_waitcnt lgkmcnt(0)
	v_add_f32_e32 v135, v135, v136
	s_nop 1
	v_mov_b32_dpp v136, v135 row_half_mirror row_mask:0xf bank_mask:0xf
	s_nop 1
	v_mov_b32_dpp v137, v134 row_mirror row_mask:0xf bank_mask:0xf
	s_waitcnt lgkmcnt(0)
	v_add_f32_e32 v132, v132, v133
	s_nop 1
	v_mov_b32_dpp v133, v132 row_half_mirror row_mask:0xf bank_mask:0xf
	s_waitcnt lgkmcnt(0)
	v_add_f32_e32 v131, v135, v136
	s_waitcnt lgkmcnt(0)
	v_add_f32_e32 v127, v134, v137
	s_nop 1
	v_mov_b32_dpp v134, v131 row_mirror row_mask:0xf bank_mask:0xf
	s_waitcnt lgkmcnt(0)
	v_add_f32_e32 v135, v132, v133
	v_mov_b32_e32 v132, v97
	v_mov_b32_e32 v97, v99
	v_mov_b32_e32 v133, v98
	v_pk_mul_f32 v[96:97], v[96:97], v[112:113]
	s_nop 1
	v_mov_b32_dpp v136, v135 row_mirror row_mask:0xf bank_mask:0xf
	v_pk_fma_f32 v[96:97], v[132:133], v[108:109], v[96:97]
	s_nop 0
	v_add_f32_e32 v98, v96, v97
	v_mov_b32_e32 v96, v93
	v_mov_b32_e32 v93, v95
	v_mov_b32_e32 v97, v94
	v_pk_mul_f32 v[92:93], v[92:93], v[112:113]
	s_nop 1
	v_mov_b32_dpp v99, v98 quad_perm:[1,0,3,2] row_mask:0xf bank_mask:0xf
	v_pk_fma_f32 v[92:93], v[96:97], v[108:109], v[92:93]
	s_waitcnt lgkmcnt(0)
	v_add_f32_e32 v96, v98, v99
	v_add_f32_e32 v94, v92, v93
	s_nop 1
	v_mov_b32_dpp v95, v94 quad_perm:[1,0,3,2] row_mask:0xf bank_mask:0xf
	s_nop 1
	v_mov_b32_dpp v97, v96 quad_perm:[2,3,0,1] row_mask:0xf bank_mask:0xf
	v_add_f32_e32 v93, v131, v134
	v_add_f32_e32 v92, v135, v136
	s_waitcnt lgkmcnt(0)
	v_add_f32_e32 v98, v94, v95
	v_mov_b32_e32 v94, v89
	v_mov_b32_e32 v89, v91
	v_mov_b32_e32 v95, v90
	v_pk_mul_f32 v[88:89], v[88:89], v[112:113]
	s_waitcnt lgkmcnt(0)
	v_add_f32_e32 v90, v96, v97
	v_pk_fma_f32 v[88:89], v[94:95], v[108:109], v[88:89]
	s_nop 1
	v_mov_b32_dpp v91, v90 row_half_mirror row_mask:0xf bank_mask:0xf
	v_add_f32_e32 v88, v88, v89
	s_nop 1
	v_mov_b32_dpp v89, v88 quad_perm:[1,0,3,2] row_mask:0xf bank_mask:0xf
	s_nop 1
	v_mov_b32_dpp v99, v98 quad_perm:[2,3,0,1] row_mask:0xf bank_mask:0xf
	s_waitcnt lgkmcnt(0)
	v_add_f32_e32 v90, v90, v91
	s_nop 1
	v_mov_b32_dpp v91, v90 row_mirror row_mask:0xf bank_mask:0xf
	s_waitcnt lgkmcnt(0)
	v_add_f32_e32 v88, v88, v89
	s_nop 1
	v_mov_b32_dpp v89, v88 quad_perm:[2,3,0,1] row_mask:0xf bank_mask:0xf
	s_waitcnt lgkmcnt(0)
	v_add_f32_e32 v94, v98, v99
	s_nop 1
	v_mov_b32_dpp v95, v94 row_half_mirror row_mask:0xf bank_mask:0xf
	s_waitcnt lgkmcnt(0)
	v_add_f32_e32 v96, v88, v89
	v_mov_b32_e32 v88, v85
	v_mov_b32_e32 v85, v87
	v_mov_b32_e32 v89, v86
	v_pk_mul_f32 v[84:85], v[84:85], v[112:113]
	s_nop 1
	v_mov_b32_dpp v97, v96 row_half_mirror row_mask:0xf bank_mask:0xf
	v_pk_fma_f32 v[84:85], v[88:89], v[108:109], v[84:85]
	s_waitcnt lgkmcnt(0)
	v_add_f32_e32 v94, v94, v95
	v_add_f32_e32 v86, v84, v85
	s_nop 1
	v_mov_b32_dpp v87, v86 quad_perm:[1,0,3,2] row_mask:0xf bank_mask:0xf
	v_add_f32_e32 v85, v90, v91
	s_waitcnt lgkmcnt(0)
	v_add_f32_e32 v88, v96, v97
	s_nop 1
	v_mov_b32_dpp v95, v94 row_mirror row_mask:0xf bank_mask:0xf
	s_nop 1
	v_mov_b32_dpp v89, v88 row_mirror row_mask:0xf bank_mask:0xf
	s_waitcnt lgkmcnt(0)
	v_add_f32_e32 v90, v86, v87
	v_mov_b32_e32 v86, v81
	v_mov_b32_e32 v81, v83
	s_nop 1
	v_mov_b32_dpp v91, v90 quad_perm:[2,3,0,1] row_mask:0xf bank_mask:0xf
	v_mov_b32_e32 v87, v82
	v_pk_mul_f32 v[80:81], v[80:81], v[112:113]
	s_waitcnt lgkmcnt(0)
	v_add_f32_e32 v84, v94, v95
	v_pk_fma_f32 v[80:81], v[86:87], v[108:109], v[80:81]
	s_nop 0
	v_add_f32_e32 v82, v80, v81
	v_mov_b32_e32 v80, v77
	v_mov_b32_e32 v77, v79
	v_mov_b32_e32 v81, v78
	v_pk_mul_f32 v[76:77], v[76:77], v[112:113]
	s_waitcnt lgkmcnt(0)
	v_add_f32_e32 v78, v90, v91
	v_pk_fma_f32 v[76:77], v[80:81], v[108:109], v[76:77]
	s_nop 1
	v_mov_b32_dpp v79, v78 row_half_mirror row_mask:0xf bank_mask:0xf
	v_add_f32_e32 v76, v76, v77
	s_nop 1
	v_mov_b32_dpp v77, v76 quad_perm:[1,0,3,2] row_mask:0xf bank_mask:0xf
	s_nop 1
	v_mov_b32_dpp v83, v82 quad_perm:[1,0,3,2] row_mask:0xf bank_mask:0xf
	s_waitcnt lgkmcnt(0)
	v_add_f32_e32 v78, v78, v79
	s_nop 1
	v_mov_b32_dpp v79, v78 row_mirror row_mask:0xf bank_mask:0xf
	s_waitcnt lgkmcnt(0)
	v_add_f32_e32 v76, v76, v77
	s_nop 1
	v_mov_b32_dpp v77, v76 quad_perm:[2,3,0,1] row_mask:0xf bank_mask:0xf
	s_waitcnt lgkmcnt(0)
	v_add_f32_e32 v80, v82, v83
	s_nop 1
	v_mov_b32_dpp v81, v80 quad_perm:[2,3,0,1] row_mask:0xf bank_mask:0xf
	s_waitcnt lgkmcnt(0)
	v_add_f32_e32 v82, v76, v77
	v_add_f32_e32 v76, v78, v79
	v_mov_b32_e32 v78, v73
	v_mov_b32_e32 v73, v75
	v_mov_b32_e32 v79, v74
	v_pk_mul_f32 v[72:73], v[72:73], v[112:113]
	s_nop 1
	v_mov_b32_dpp v83, v82 row_half_mirror row_mask:0xf bank_mask:0xf
	v_pk_fma_f32 v[72:73], v[78:79], v[108:109], v[72:73]
	s_waitcnt lgkmcnt(0)
	v_add_f32_e32 v80, v80, v81
	v_add_f32_e32 v74, v72, v73
	v_mov_b32_e32 v72, v69
	v_mov_b32_e32 v69, v71
	v_mov_b32_e32 v73, v70
	v_pk_mul_f32 v[68:69], v[68:69], v[112:113]
	s_nop 1
	v_mov_b32_dpp v75, v74 quad_perm:[1,0,3,2] row_mask:0xf bank_mask:0xf
	v_pk_fma_f32 v[68:69], v[72:73], v[108:109], v[68:69]
	s_waitcnt lgkmcnt(0)
	v_add_f32_e32 v82, v82, v83
	v_add_f32_e32 v70, v68, v69
	s_nop 1
	v_mov_b32_dpp v71, v70 quad_perm:[1,0,3,2] row_mask:0xf bank_mask:0xf
	s_waitcnt lgkmcnt(0)
	v_add_f32_e32 v72, v74, v75
	s_nop 1
	v_mov_b32_dpp v73, v72 quad_perm:[2,3,0,1] row_mask:0xf bank_mask:0xf
	s_nop 1
	v_mov_b32_dpp v83, v82 row_mirror row_mask:0xf bank_mask:0xf
	s_nop 1
	v_mov_b32_dpp v81, v80 row_half_mirror row_mask:0xf bank_mask:0xf
	s_waitcnt lgkmcnt(0)
	v_add_f32_e32 v74, v70, v71
	v_mov_b32_e32 v70, v65
	v_mov_b32_e32 v65, v67
	v_mov_b32_e32 v71, v66
	v_pk_mul_f32 v[64:65], v[64:65], v[112:113]
	s_waitcnt lgkmcnt(0)
	v_add_f32_e32 v66, v72, v73
	v_pk_fma_f32 v[64:65], v[70:71], v[108:109], v[64:65]
	s_nop 1
	v_mov_b32_dpp v67, v66 row_half_mirror row_mask:0xf bank_mask:0xf
	v_add_f32_e32 v64, v64, v65
	s_nop 1
	v_mov_b32_dpp v65, v64 quad_perm:[1,0,3,2] row_mask:0xf bank_mask:0xf
	s_nop 1
	v_mov_b32_dpp v75, v74 quad_perm:[2,3,0,1] row_mask:0xf bank_mask:0xf
	s_waitcnt lgkmcnt(0)
	v_add_f32_e32 v68, v82, v83
	s_waitcnt lgkmcnt(0)
	v_add_f32_e32 v66, v66, v67
	s_nop 1
	v_mov_b32_dpp v67, v66 row_mirror row_mask:0xf bank_mask:0xf
	s_waitcnt lgkmcnt(0)
	v_add_f32_e32 v64, v64, v65
	s_nop 1
	v_mov_b32_dpp v65, v64 quad_perm:[2,3,0,1] row_mask:0xf bank_mask:0xf
	s_waitcnt lgkmcnt(0)
	v_add_f32_e32 v70, v74, v75
	s_nop 1
	v_mov_b32_dpp v71, v70 row_half_mirror row_mask:0xf bank_mask:0xf
	s_waitcnt lgkmcnt(0)
	v_add_f32_e32 v66, v66, v67
	v_add_f32_e32 v80, v80, v81
	s_waitcnt lgkmcnt(0)
	v_add_f32_e32 v72, v64, v65
	v_mov_b32_e32 v64, v61
	v_mov_b32_e32 v61, v63
	v_mov_b32_e32 v65, v62
	v_pk_mul_f32 v[60:61], v[60:61], v[112:113]
	s_nop 1
	v_mov_b32_dpp v81, v80 row_mirror row_mask:0xf bank_mask:0xf
	v_pk_fma_f32 v[60:61], v[64:65], v[108:109], v[60:61]
	s_nop 1
	v_mov_b32_dpp v73, v72 row_half_mirror row_mask:0xf bank_mask:0xf
	v_add_f32_e32 v60, v60, v61
	s_nop 1
	v_mov_b32_dpp v61, v60 quad_perm:[1,0,3,2] row_mask:0xf bank_mask:0xf
	s_waitcnt lgkmcnt(0)
	v_add_f32_e32 v70, v70, v71
	s_nop 1
	v_mov_b32_dpp v71, v70 row_mirror row_mask:0xf bank_mask:0xf
	v_add_f32_e32 v77, v88, v89
	s_waitcnt lgkmcnt(0)
	v_add_f32_e32 v69, v80, v81
	s_waitcnt lgkmcnt(0)
	v_add_f32_e32 v65, v60, v61
	v_mov_b32_e32 v60, v57
	v_mov_b32_e32 v57, v59
	v_mov_b32_e32 v61, v58
	v_pk_mul_f32 v[56:57], v[56:57], v[112:113]
	s_nop 1
	v_mov_b32_dpp v67, v65 quad_perm:[2,3,0,1] row_mask:0xf bank_mask:0xf
	v_pk_fma_f32 v[56:57], v[60:61], v[108:109], v[56:57]
	v_add_f32_e32 v62, v72, v73
	v_add_f32_e32 v58, v56, v57
	v_mov_b32_e32 v56, v53
	v_mov_b32_e32 v53, v55
	v_mov_b32_e32 v57, v54
	v_pk_mul_f32 v[52:53], v[52:53], v[112:113]
	s_nop 1
	v_mov_b32_dpp v59, v58 quad_perm:[1,0,3,2] row_mask:0xf bank_mask:0xf
	v_pk_fma_f32 v[52:53], v[56:57], v[108:109], v[52:53]
	s_waitcnt lgkmcnt(0)
	v_add_f32_e32 v54, v65, v67
	v_add_f32_e32 v52, v52, v53
	s_nop 1
	v_mov_b32_dpp v53, v52 quad_perm:[1,0,3,2] row_mask:0xf bank_mask:0xf
	s_waitcnt lgkmcnt(0)
	v_add_f32_e32 v56, v58, v59
	s_nop 1
	v_mov_b32_dpp v55, v54 row_half_mirror row_mask:0xf bank_mask:0xf
	s_nop 1
	v_mov_b32_dpp v57, v56 quad_perm:[2,3,0,1] row_mask:0xf bank_mask:0xf
	s_nop 1
	v_mov_b32_dpp v63, v62 row_mirror row_mask:0xf bank_mask:0xf
	s_waitcnt lgkmcnt(0)
	v_add_f32_e32 v52, v52, v53
	s_nop 1
	v_mov_b32_dpp v53, v52 quad_perm:[2,3,0,1] row_mask:0xf bank_mask:0xf
	s_waitcnt lgkmcnt(0)
	v_add_f32_e32 v54, v54, v55
	s_waitcnt lgkmcnt(0)
	v_add_f32_e32 v56, v56, v57
	s_nop 1
	v_mov_b32_dpp v55, v54 row_mirror row_mask:0xf bank_mask:0xf
	s_nop 1
	v_mov_b32_dpp v57, v56 row_half_mirror row_mask:0xf bank_mask:0xf
	s_waitcnt lgkmcnt(0)
	v_add_f32_e32 v52, v52, v53
	s_nop 1
	v_mov_b32_dpp v53, v52 row_half_mirror row_mask:0xf bank_mask:0xf
	v_add_f32_e32 v64, v70, v71
	s_waitcnt lgkmcnt(0)
	v_add_f32_e32 v58, v54, v55
	s_waitcnt lgkmcnt(0)
	v_add_f32_e32 v54, v56, v57
	s_nop 1
	v_mov_b32_dpp v55, v54 row_mirror row_mask:0xf bank_mask:0xf
	s_waitcnt lgkmcnt(0)
	v_add_f32_e32 v56, v52, v53
	v_mov_b32_e32 v52, v49
	v_mov_b32_e32 v49, v51
	v_mov_b32_e32 v53, v50
	v_pk_mul_f32 v[48:49], v[48:49], v[112:113]
	s_waitcnt lgkmcnt(0)
	v_add_f32_e32 v61, v54, v55
	v_pk_fma_f32 v[48:49], v[52:53], v[108:109], v[48:49]
	s_nop 1
	v_mov_b32_dpp v57, v56 row_mirror row_mask:0xf bank_mask:0xf
	v_add_f32_e32 v50, v48, v49
	v_mov_b32_e32 v48, v45
	v_mov_b32_e32 v45, v47
	v_mov_b32_e32 v49, v46
	v_pk_mul_f32 v[44:45], v[44:45], v[112:113]
	s_nop 1
	v_mov_b32_dpp v51, v50 quad_perm:[1,0,3,2] row_mask:0xf bank_mask:0xf
	v_pk_fma_f32 v[44:45], v[48:49], v[108:109], v[44:45]
	s_waitcnt lgkmcnt(0)
	v_add_f32_e32 v57, v56, v57
	v_add_f32_e32 v44, v44, v45
	s_nop 1
	v_mov_b32_dpp v45, v44 quad_perm:[1,0,3,2] row_mask:0xf bank_mask:0xf
	s_waitcnt lgkmcnt(0)
	v_add_f32_e32 v46, v50, v51
	s_nop 1
	v_mov_b32_dpp v47, v46 quad_perm:[2,3,0,1] row_mask:0xf bank_mask:0xf
	v_add_f32_e32 v62, v62, v63
	s_waitcnt lgkmcnt(0)
	v_add_f32_e32 v48, v44, v45
	v_mov_b32_e32 v44, v41
	v_mov_b32_e32 v41, v43
	v_mov_b32_e32 v45, v42
	v_pk_mul_f32 v[40:41], v[40:41], v[112:113]
	s_waitcnt lgkmcnt(0)
	v_add_f32_e32 v42, v46, v47
	v_pk_fma_f32 v[40:41], v[44:45], v[108:109], v[40:41]
	s_nop 1
	v_mov_b32_dpp v49, v48 quad_perm:[2,3,0,1] row_mask:0xf bank_mask:0xf
	v_add_f32_e32 v40, v40, v41
	s_nop 1
	v_mov_b32_dpp v41, v40 quad_perm:[1,0,3,2] row_mask:0xf bank_mask:0xf
	s_nop 1
	v_mov_b32_dpp v43, v42 row_half_mirror row_mask:0xf bank_mask:0xf
	s_waitcnt lgkmcnt(0)
	v_add_f32_e32 v44, v48, v49
	s_nop 1
	v_mov_b32_dpp v45, v44 row_half_mirror row_mask:0xf bank_mask:0xf
	s_waitcnt lgkmcnt(0)
	v_add_f32_e32 v40, v40, v41
	s_nop 1
	v_mov_b32_dpp v41, v40 quad_perm:[2,3,0,1] row_mask:0xf bank_mask:0xf
	v_lshl_add_u64 v[48:49], v[102:103], 0, v[110:111]
	s_waitcnt lgkmcnt(0)
	v_add_f32_e32 v42, v42, v43
	s_waitcnt lgkmcnt(0)
	v_add_f32_e32 v44, v44, v45
	s_nop 1
	v_mov_b32_dpp v43, v42 row_mirror row_mask:0xf bank_mask:0xf
	s_waitcnt lgkmcnt(0)
	v_add_f32_e32 v46, v40, v41
	v_mov_b32_e32 v40, v37
	v_mov_b32_e32 v37, v39
	v_mov_b32_e32 v41, v38
	v_pk_mul_f32 v[36:37], v[36:37], v[112:113]
	s_nop 1
	v_mov_b32_dpp v45, v44 row_mirror row_mask:0xf bank_mask:0xf
	v_pk_fma_f32 v[36:37], v[40:41], v[108:109], v[36:37]
	s_nop 1
	v_mov_b32_dpp v47, v46 row_half_mirror row_mask:0xf bank_mask:0xf
	v_add_f32_e32 v36, v36, v37
	s_nop 1
	v_mov_b32_dpp v37, v36 quad_perm:[1,0,3,2] row_mask:0xf bank_mask:0xf
	s_waitcnt lgkmcnt(0)
	v_add_f32_e32 v60, v42, v43
	s_waitcnt lgkmcnt(0)
	v_add_f32_e32 v56, v44, v45
	s_waitcnt lgkmcnt(0)
	v_add_f32_e32 v38, v46, v47
	global_load_dwordx4 v[78:81], v[48:49], off
	global_load_dwordx4 v[86:89], v[48:49], off offset:2048
	s_waitcnt lgkmcnt(0)
	v_add_f32_e32 v40, v36, v37
	v_mov_b32_e32 v36, v33
	v_mov_b32_e32 v33, v35
	v_mov_b32_e32 v37, v34
	v_pk_mul_f32 v[32:33], v[32:33], v[112:113]
	s_nop 1
	v_mov_b32_dpp v41, v40 quad_perm:[2,3,0,1] row_mask:0xf bank_mask:0xf
	v_pk_fma_f32 v[32:33], v[36:37], v[108:109], v[32:33]
	s_nop 1
	v_mov_b32_dpp v39, v38 row_mirror row_mask:0xf bank_mask:0xf
	v_add_f32_e32 v34, v32, v33
	v_mov_b32_e32 v32, v29
	v_mov_b32_e32 v29, v31
	v_mov_b32_e32 v33, v30
	v_pk_mul_f32 v[28:29], v[28:29], v[112:113]
	s_nop 1
	v_mov_b32_dpp v35, v34 quad_perm:[1,0,3,2] row_mask:0xf bank_mask:0xf
	v_pk_fma_f32 v[28:29], v[32:33], v[108:109], v[28:29]
	s_waitcnt lgkmcnt(0)
	v_add_f32_e32 v30, v40, v41
	v_add_f32_e32 v28, v28, v29
	s_nop 1
	v_mov_b32_dpp v29, v28 quad_perm:[1,0,3,2] row_mask:0xf bank_mask:0xf
	s_waitcnt lgkmcnt(0)
	v_add_f32_e32 v32, v34, v35
	s_nop 1
	v_mov_b32_dpp v33, v32 quad_perm:[2,3,0,1] row_mask:0xf bank_mask:0xf
	s_nop 1
	v_mov_b32_dpp v31, v30 row_half_mirror row_mask:0xf bank_mask:0xf
	v_add_f32_e32 v63, v38, v39
	s_waitcnt lgkmcnt(0)
	v_add_f32_e32 v28, v28, v29
	s_nop 1
	v_mov_b32_dpp v29, v28 quad_perm:[2,3,0,1] row_mask:0xf bank_mask:0xf
	s_waitcnt lgkmcnt(0)
	v_add_f32_e32 v32, v32, v33
	s_nop 1
	v_mov_b32_dpp v33, v32 row_half_mirror row_mask:0xf bank_mask:0xf
	s_waitcnt lgkmcnt(0)
	v_add_f32_e32 v30, v30, v31
	s_nop 1
	v_mov_b32_dpp v31, v30 row_mirror row_mask:0xf bank_mask:0xf
	s_waitcnt lgkmcnt(0)
	v_add_f32_e32 v34, v28, v29
	v_mov_b32_e32 v28, v25
	v_mov_b32_e32 v25, v27
	v_mov_b32_e32 v29, v26
	v_pk_mul_f32 v[24:25], v[24:25], v[112:113]
	s_waitcnt lgkmcnt(0)
	v_add_f32_e32 v26, v32, v33
	v_pk_fma_f32 v[24:25], v[28:29], v[108:109], v[24:25]
	s_nop 1
	v_mov_b32_dpp v27, v26 row_mirror row_mask:0xf bank_mask:0xf
	v_add_f32_e32 v24, v24, v25
	s_nop 1
	v_mov_b32_dpp v25, v24 quad_perm:[1,0,3,2] row_mask:0xf bank_mask:0xf
	s_nop 1
	v_mov_b32_dpp v35, v34 row_half_mirror row_mask:0xf bank_mask:0xf
	s_waitcnt lgkmcnt(0)
	v_add_f32_e32 v59, v30, v31
	s_waitcnt lgkmcnt(0)
	v_add_f32_e32 v54, v26, v27
	s_waitcnt lgkmcnt(0)
	v_add_f32_e32 v24, v24, v25
	s_nop 1
	v_mov_b32_dpp v25, v24 quad_perm:[2,3,0,1] row_mask:0xf bank_mask:0xf
	s_waitcnt lgkmcnt(0)
	v_add_f32_e32 v28, v34, v35
	s_nop 1
	v_mov_b32_dpp v29, v28 row_mirror row_mask:0xf bank_mask:0xf
	s_waitcnt lgkmcnt(0)
	v_add_f32_e32 v26, v24, v25
	v_mov_b32_e32 v24, v21
	v_mov_b32_e32 v21, v23
	v_mov_b32_e32 v25, v22
	v_pk_mul_f32 v[20:21], v[20:21], v[112:113]
	s_nop 1
	v_mov_b32_dpp v27, v26 row_half_mirror row_mask:0xf bank_mask:0xf
	v_pk_fma_f32 v[20:21], v[24:25], v[108:109], v[20:21]
	s_waitcnt lgkmcnt(0)
	v_add_f32_e32 v52, v28, v29
	v_add_f32_e32 v22, v20, v21
	v_mov_b32_e32 v20, v17
	v_mov_b32_e32 v17, v19
	v_mov_b32_e32 v21, v18
	v_pk_mul_f32 v[16:17], v[16:17], v[112:113]
	s_nop 1
	v_mov_b32_dpp v23, v22 quad_perm:[1,0,3,2] row_mask:0xf bank_mask:0xf
	v_pk_fma_f32 v[16:17], v[20:21], v[108:109], v[16:17]
	s_waitcnt lgkmcnt(0)
	v_add_f32_e32 v53, v26, v27
	v_add_f32_e32 v16, v16, v17
	s_nop 1
	v_mov_b32_dpp v17, v16 quad_perm:[1,0,3,2] row_mask:0xf bank_mask:0xf
	s_waitcnt lgkmcnt(0)
	v_add_f32_e32 v18, v22, v23
	s_nop 1
	v_mov_b32_dpp v19, v18 quad_perm:[2,3,0,1] row_mask:0xf bank_mask:0xf
	s_nop 1
	v_mov_b32_dpp v55, v53 row_mirror row_mask:0xf bank_mask:0xf
	s_waitcnt lgkmcnt(0)
	v_add_f32_e32 v20, v16, v17
	v_mov_b32_e32 v16, v13
	v_mov_b32_e32 v13, v15
	v_mov_b32_e32 v17, v14
	v_pk_mul_f32 v[12:13], v[12:13], v[112:113]
	s_nop 1
	v_mov_b32_dpp v21, v20 quad_perm:[2,3,0,1] row_mask:0xf bank_mask:0xf
	v_pk_fma_f32 v[12:13], v[16:17], v[108:109], v[12:13]
	s_waitcnt lgkmcnt(0)
	v_add_f32_e32 v14, v18, v19
	v_add_f32_e32 v12, v12, v13
	s_nop 1
	v_mov_b32_dpp v13, v12 quad_perm:[1,0,3,2] row_mask:0xf bank_mask:0xf
	s_nop 1
	v_mov_b32_dpp v15, v14 row_half_mirror row_mask:0xf bank_mask:0xf
	s_waitcnt lgkmcnt(0)
	v_add_f32_e32 v16, v20, v21
	s_nop 1
	v_mov_b32_dpp v17, v16 row_half_mirror row_mask:0xf bank_mask:0xf
	v_add_f32_e32 v73, v53, v55
	s_waitcnt lgkmcnt(0)
	v_add_f32_e32 v12, v12, v13
	s_nop 1
	v_mov_b32_dpp v13, v12 quad_perm:[2,3,0,1] row_mask:0xf bank_mask:0xf
	s_waitcnt lgkmcnt(0)
	v_add_f32_e32 v65, v14, v15
	s_waitcnt lgkmcnt(0)
	v_add_f32_e32 v74, v16, v17
	s_nop 1
	v_mov_b32_dpp v75, v74 row_mirror row_mask:0xf bank_mask:0xf
	s_nop 1
	v_mov_b32_dpp v67, v65 row_mirror row_mask:0xf bank_mask:0xf
	s_waitcnt lgkmcnt(0)
	v_add_f32_e32 v82, v12, v13
	v_add_co_u32_e32 v12, vcc, s17, v48
	s_nop 1
	v_mov_b32_dpp v83, v82 row_half_mirror row_mask:0xf bank_mask:0xf
	s_nop 0
	v_addc_co_u32_e32 v13, vcc, 0, v49, vcc
	v_add_co_u32_e32 v14, vcc, s91, v48
	s_waitcnt lgkmcnt(0)
	v_add_f32_e32 v53, v82, v83
	v_addc_co_u32_e32 v15, vcc, 0, v49, vcc
	v_add_co_u32_e32 v16, vcc, s50, v48
	global_load_dwordx4 v[94:97], v[14:15], off offset:-4096
	global_load_dwordx4 v[132:135], v[14:15], off
	v_addc_co_u32_e32 v17, vcc, 0, v49, vcc
	v_add_co_u32_e32 v18, vcc, s90, v48
	s_nop 1
	v_mov_b32_dpp v55, v53 row_mirror row_mask:0xf bank_mask:0xf
	s_nop 0
	v_addc_co_u32_e32 v19, vcc, 0, v49, vcc
	global_load_dwordx4 v[136:139], v[14:15], off offset:2048
	global_load_dwordx4 v[140:143], v[18:19], off offset:-4096
	global_load_dwordx4 v[144:147], v[12:13], off offset:2048
	global_load_dwordx4 v[44:47], v[16:17], off offset:2048
	global_load_dwordx4 v[40:43], v[18:19], off
	global_load_dwordx4 v[32:35], v[18:19], off offset:2048
	v_add_co_u32_e32 v12, vcc, s96, v48
	v_add_f32_e32 v72, v65, v67
	s_nop 0
	v_addc_co_u32_e32 v13, vcc, 0, v49, vcc
	v_add_co_u32_e32 v14, vcc, s21, v48
	s_nop 1
	v_addc_co_u32_e32 v15, vcc, 0, v49, vcc
	v_add_co_u32_e32 v70, vcc, s51, v48
	global_load_dwordx4 v[36:39], v[14:15], off offset:-4096
	global_load_dwordx4 v[24:27], v[14:15], off
	v_addc_co_u32_e32 v71, vcc, 0, v49, vcc
	v_add_co_u32_e32 v50, vcc, s92, v48
	s_nop 1
	v_addc_co_u32_e32 v51, vcc, 0, v49, vcc
	global_load_dwordx4 v[20:23], v[14:15], off offset:2048
	global_load_dwordx4 v[16:19], v[50:51], off offset:-4096
	global_load_dwordx4 v[28:31], v[12:13], off offset:2048
	s_nop 0
	global_load_dwordx4 v[12:15], v[70:71], off offset:2048
	v_add_f32_e32 v70, v74, v75
	v_mov_b32_e32 v74, v9
	v_mov_b32_e32 v9, v11
	v_mov_b32_e32 v75, v10
	v_pk_mul_f32 v[8:9], v[8:9], v[112:113]
	s_waitcnt lgkmcnt(0)
	v_add_f32_e32 v71, v53, v55
	v_pk_fma_f32 v[8:9], v[74:75], v[108:109], v[8:9]
	s_nop 0
	v_add_f32_e32 v10, v8, v9
	s_waitcnt vmcnt(16)
	v_mov_b32_e32 v8, v5
	v_mov_b32_e32 v9, v6
	v_mov_b32_e32 v5, v7
	v_mul_f32_e32 v6, v108, v123
	v_mul_f32_e32 v7, v113, v124
	v_pk_mul_f32 v[4:5], v[4:5], v[112:113]
	v_fmac_f32_e32 v6, v112, v121
	v_fmac_f32_e32 v7, v109, v122
	v_pk_fma_f32 v[4:5], v[8:9], v[108:109], v[4:5]
	v_add_f32_e32 v6, v6, v7
	v_add_f32_e32 v4, v4, v5
	s_nop 1
	v_mov_b32_dpp v7, v6 quad_perm:[1,0,3,2] row_mask:0xf bank_mask:0xf
	s_nop 1
	v_mov_b32_dpp v5, v4 quad_perm:[1,0,3,2] row_mask:0xf bank_mask:0xf
	s_nop 1
	v_mov_b32_dpp v11, v10 quad_perm:[1,0,3,2] row_mask:0xf bank_mask:0xf
	s_waitcnt lgkmcnt(0)
	v_add_f32_e32 v6, v6, v7
	s_waitcnt lgkmcnt(0)
	v_add_f32_e32 v4, v4, v5
	s_nop 1
	v_mov_b32_dpp v7, v6 quad_perm:[2,3,0,1] row_mask:0xf bank_mask:0xf
	s_nop 1
	v_mov_b32_dpp v5, v4 quad_perm:[2,3,0,1] row_mask:0xf bank_mask:0xf
	s_waitcnt lgkmcnt(0)
	v_add_f32_e32 v8, v10, v11
	s_nop 1
	v_mov_b32_dpp v9, v8 quad_perm:[2,3,0,1] row_mask:0xf bank_mask:0xf
	s_waitcnt lgkmcnt(0)
	v_add_f32_e32 v6, v6, v7
	s_waitcnt lgkmcnt(0)
	v_add_f32_e32 v4, v4, v5
	s_nop 1
	v_mov_b32_dpp v7, v6 row_half_mirror row_mask:0xf bank_mask:0xf
	s_nop 1
	v_mov_b32_dpp v5, v4 row_half_mirror row_mask:0xf bank_mask:0xf
	s_waitcnt lgkmcnt(0)
	v_add_f32_e32 v8, v8, v9
	s_nop 1
	v_mov_b32_dpp v9, v8 row_half_mirror row_mask:0xf bank_mask:0xf
	s_waitcnt lgkmcnt(0)
	v_add_f32_e32 v6, v6, v7
	s_waitcnt lgkmcnt(0)
	v_add_f32_e32 v4, v4, v5
	s_nop 1
	v_mov_b32_dpp v7, v6 row_mirror row_mask:0xf bank_mask:0xf
	s_nop 1
	v_mov_b32_dpp v5, v4 row_mirror row_mask:0xf bank_mask:0xf
	s_waitcnt lgkmcnt(0)
	v_add_f32_e32 v8, v8, v9
	s_nop 1
	v_mov_b32_dpp v9, v8 row_mirror row_mask:0xf bank_mask:0xf
	s_waitcnt lgkmcnt(0)
	v_add_f32_e32 v53, v6, v7
	s_waitcnt lgkmcnt(0)
	v_add_f32_e32 v65, v4, v5
	v_cndmask_b32_e64 v4, v130, v237, s[38:39]
	v_max_f32_e32 v5, v53, v120
	v_max3_f32 v5, v5, v4, v126
	v_max3_f32 v5, v5, v128, v125
	v_max3_f32 v5, v5, v129, v127
	v_max3_f32 v5, v5, v93, v92
	v_max3_f32 v5, v5, v85, v84
	v_max3_f32 v5, v5, v77, v76
	v_max3_f32 v5, v5, v69, v68
	v_max3_f32 v5, v5, v66, v64
	v_max3_f32 v5, v5, v62, v58
	v_max3_f32 v5, v5, v61, v57
	v_max3_f32 v5, v5, v60, v56
	v_max3_f32 v5, v5, v63, v59
	v_max3_f32 v5, v5, v54, v52
	v_max3_f32 v5, v5, v73, v72
	s_waitcnt lgkmcnt(0)
	v_add_f32_e32 v67, v8, v9
	v_max3_f32 v5, v5, v70, v71
	v_max3_f32 v5, v5, v67, v65
	ds_bpermute_b32 v6, v118, v5
	s_waitcnt lgkmcnt(0)
	v_max_f32_e32 v6, v6, v6
	v_max_f32_e32 v5, v5, v6
	ds_bpermute_b32 v6, v119, v5
	s_waitcnt lgkmcnt(0)
	v_max_f32_e32 v6, v6, v6
	v_max_f32_e32 v55, v5, v6
	v_sub_f32_e32 v4, v4, v55
	v_exp_f32_e32 v4, v4
	v_sub_f32_e32 v8, v126, v55
	v_exp_f32_e32 v8, v8
	v_add_f32_e32 v9, 0, v4
	s_waitcnt vmcnt(15)
	v_pk_fma_f32 v[6:7], v[78:79], v[4:5], 0 op_sel_hi:[1,0,0]
	v_pk_fma_f32 v[4:5], v[80:81], v[4:5], 0 op_sel_hi:[1,0,0]
	v_add_f32_e32 v9, v8, v9
	s_waitcnt vmcnt(14)
	v_pk_fma_f32 v[4:5], v[88:89], v[8:9], v[4:5] op_sel_hi:[1,0,1]
	v_pk_fma_f32 v[6:7], v[86:87], v[8:9], v[6:7] op_sel_hi:[1,0,1]
	v_sub_f32_e32 v8, v128, v55
	v_exp_f32_e32 v8, v8
	s_nop 0
	v_add_f32_e32 v9, v8, v9
	s_waitcnt vmcnt(13)
	v_pk_fma_f32 v[6:7], v[94:95], v[8:9], v[6:7] op_sel_hi:[1,0,1]
	v_pk_fma_f32 v[4:5], v[96:97], v[8:9], v[4:5] op_sel_hi:[1,0,1]
	v_sub_f32_e32 v8, v125, v55
	v_exp_f32_e32 v8, v8
	s_nop 0
	v_add_f32_e32 v9, v8, v9
	s_waitcnt vmcnt(9)
	v_pk_fma_f32 v[4:5], v[146:147], v[8:9], v[4:5] op_sel_hi:[1,0,1]
	v_pk_fma_f32 v[6:7], v[144:145], v[8:9], v[6:7] op_sel_hi:[1,0,1]
	v_sub_f32_e32 v8, v129, v55
	v_exp_f32_e32 v8, v8
	s_nop 0
	v_add_f32_e32 v9, v8, v9
	v_pk_fma_f32 v[6:7], v[132:133], v[8:9], v[6:7] op_sel_hi:[1,0,1]
	v_pk_fma_f32 v[4:5], v[134:135], v[8:9], v[4:5] op_sel_hi:[1,0,1]
	v_sub_f32_e32 v8, v127, v55
	v_exp_f32_e32 v8, v8
	s_nop 0
	v_add_f32_e32 v9, v8, v9
	v_pk_fma_f32 v[4:5], v[138:139], v[8:9], v[4:5] op_sel_hi:[1,0,1]
	v_pk_fma_f32 v[6:7], v[136:137], v[8:9], v[6:7] op_sel_hi:[1,0,1]
	v_sub_f32_e32 v8, v93, v55
	v_exp_f32_e32 v8, v8
	s_nop 0
	v_add_f32_e32 v9, v8, v9
	v_pk_fma_f32 v[6:7], v[140:141], v[8:9], v[6:7] op_sel_hi:[1,0,1]
	v_pk_fma_f32 v[4:5], v[142:143], v[8:9], v[4:5] op_sel_hi:[1,0,1]
	v_sub_f32_e32 v8, v92, v55
	v_exp_f32_e32 v8, v8
	s_nop 0
	v_add_f32_e32 v9, v8, v9
	s_waitcnt vmcnt(8)
	v_pk_fma_f32 v[4:5], v[46:47], v[8:9], v[4:5] op_sel_hi:[1,0,1]
	v_pk_fma_f32 v[6:7], v[44:45], v[8:9], v[6:7] op_sel_hi:[1,0,1]
	v_sub_f32_e32 v8, v85, v55
	v_exp_f32_e32 v8, v8
	s_nop 0
	v_add_f32_e32 v9, v8, v9
	s_waitcnt vmcnt(7)
	v_pk_fma_f32 v[6:7], v[40:41], v[8:9], v[6:7] op_sel_hi:[1,0,1]
	v_pk_fma_f32 v[4:5], v[42:43], v[8:9], v[4:5] op_sel_hi:[1,0,1]
	v_sub_f32_e32 v8, v84, v55
	v_exp_f32_e32 v8, v8
	s_nop 0
	v_add_f32_e32 v9, v8, v9
	s_waitcnt vmcnt(6)
	v_pk_fma_f32 v[4:5], v[34:35], v[8:9], v[4:5] op_sel_hi:[1,0,1]
	v_pk_fma_f32 v[6:7], v[32:33], v[8:9], v[6:7] op_sel_hi:[1,0,1]
	v_sub_f32_e32 v8, v77, v55
	v_exp_f32_e32 v8, v8
	s_nop 0
	v_add_f32_e32 v9, v8, v9
	s_waitcnt vmcnt(5)
	v_pk_fma_f32 v[6:7], v[36:37], v[8:9], v[6:7] op_sel_hi:[1,0,1]
	v_pk_fma_f32 v[4:5], v[38:39], v[8:9], v[4:5] op_sel_hi:[1,0,1]
	v_sub_f32_e32 v8, v76, v55
	v_exp_f32_e32 v8, v8
	s_nop 0
	v_add_f32_e32 v9, v8, v9
	s_waitcnt vmcnt(1)
	v_pk_fma_f32 v[4:5], v[30:31], v[8:9], v[4:5] op_sel_hi:[1,0,1]
	v_pk_fma_f32 v[6:7], v[28:29], v[8:9], v[6:7] op_sel_hi:[1,0,1]
	v_sub_f32_e32 v8, v69, v55
	v_exp_f32_e32 v8, v8
	s_nop 0
	v_add_f32_e32 v9, v8, v9
	v_pk_fma_f32 v[6:7], v[24:25], v[8:9], v[6:7] op_sel_hi:[1,0,1]
	v_pk_fma_f32 v[4:5], v[26:27], v[8:9], v[4:5] op_sel_hi:[1,0,1]
	v_sub_f32_e32 v8, v68, v55
	v_exp_f32_e32 v8, v8
	s_nop 0
	v_add_f32_e32 v9, v8, v9
	v_pk_fma_f32 v[4:5], v[22:23], v[8:9], v[4:5] op_sel_hi:[1,0,1]
	v_pk_fma_f32 v[6:7], v[20:21], v[8:9], v[6:7] op_sel_hi:[1,0,1]
	v_sub_f32_e32 v8, v66, v55
	v_exp_f32_e32 v8, v8
	s_nop 0
	v_add_f32_e32 v9, v8, v9
	v_pk_fma_f32 v[6:7], v[16:17], v[8:9], v[6:7] op_sel_hi:[1,0,1]
	v_pk_fma_f32 v[4:5], v[18:19], v[8:9], v[4:5] op_sel_hi:[1,0,1]
	v_sub_f32_e32 v8, v64, v55
	v_exp_f32_e32 v8, v8
	s_nop 0
	v_add_f32_e32 v64, v8, v9
	s_waitcnt vmcnt(0)
	v_pk_fma_f32 v[68:69], v[14:15], v[8:9], v[4:5] op_sel_hi:[1,0,1]
	v_pk_fma_f32 v[90:91], v[12:13], v[8:9], v[6:7] op_sel_hi:[1,0,1]
	v_add_co_u32_e32 v4, vcc, s56, v48
	s_nop 1
	v_addc_co_u32_e32 v5, vcc, 0, v49, vcc
	v_add_co_u32_e32 v6, vcc, s93, v48
	s_nop 1
	v_addc_co_u32_e32 v7, vcc, 0, v49, vcc
	global_load_dwordx4 v[28:31], v[50:51], off offset:2048
	global_load_dwordx4 v[32:35], v[6:7], off offset:-4096
	global_load_dwordx4 v[36:39], v[6:7], off
	global_load_dwordx4 v[40:43], v[6:7], off offset:2048
	v_add_co_u32_e32 v6, vcc, s57, v48
	s_nop 1
	v_addc_co_u32_e32 v7, vcc, 0, v49, vcc
	v_add_co_u32_e32 v8, vcc, s6, v48
	s_nop 1
	v_addc_co_u32_e32 v9, vcc, 0, v49, vcc
	global_load_dwordx4 v[44:47], v[4:5], off offset:2048
	global_load_dwordx4 v[74:77], v[6:7], off offset:2048
	global_load_dwordx4 v[78:81], v[8:9], off offset:-4096
	global_load_dwordx4 v[82:85], v[8:9], off
	v_add_co_u32_e32 v4, vcc, s58, v48
	s_nop 1
	v_addc_co_u32_e32 v5, vcc, 0, v49, vcc
	v_add_co_u32_e32 v6, vcc, s95, v48
	s_nop 1
	v_addc_co_u32_e32 v7, vcc, 0, v49, vcc
	global_load_dwordx4 v[86:89], v[8:9], off offset:2048
	global_load_dwordx4 v[24:27], v[6:7], off offset:-4096
	global_load_dwordx4 v[16:19], v[6:7], off
	global_load_dwordx4 v[12:15], v[6:7], off offset:2048
	v_add_co_u32_e32 v6, vcc, s52, v48
	s_nop 1
	v_addc_co_u32_e32 v7, vcc, 0, v49, vcc
	global_load_dwordx4 v[20:23], v[4:5], off offset:2048
	global_load_dwordx4 v[8:11], v[6:7], off
	s_nop 0
	global_load_dwordx4 v[48:51], v[50:51], off
	s_nop 0
	global_load_dwordx4 v[4:7], v[6:7], off offset:2048
	v_sub_f32_e32 v62, v62, v55
	v_exp_f32_e32 v62, v62
	v_sub_f32_e32 v58, v58, v55
	v_exp_f32_e32 v58, v58
	s_waitcnt vmcnt(1)
	v_pk_fma_f32 v[48:49], v[48:49], v[62:63], v[90:91] op_sel_hi:[1,0,1]
	v_add_f32_e32 v64, v62, v64
	v_pk_fma_f32 v[28:29], v[28:29], v[58:59], v[48:49] op_sel_hi:[1,0,1]
	v_sub_f32_e32 v48, v61, v55
	v_exp_f32_e32 v48, v48
	v_pk_fma_f32 v[50:51], v[50:51], v[62:63], v[68:69] op_sel_hi:[1,0,1]
	v_add_f32_e32 v62, v58, v64
	v_pk_fma_f32 v[30:31], v[30:31], v[58:59], v[50:51] op_sel_hi:[1,0,1]
	v_add_f32_e32 v49, v48, v62
	v_pk_fma_f32 v[28:29], v[32:33], v[48:49], v[28:29] op_sel_hi:[1,0,1]
	v_sub_f32_e32 v32, v57, v55
	v_exp_f32_e32 v32, v32
	v_pk_fma_f32 v[30:31], v[34:35], v[48:49], v[30:31] op_sel_hi:[1,0,1]
	v_add_f32_e32 v33, v32, v49
	v_pk_fma_f32 v[30:31], v[46:47], v[32:33], v[30:31] op_sel_hi:[1,0,1]
	v_pk_fma_f32 v[28:29], v[44:45], v[32:33], v[28:29] op_sel_hi:[1,0,1]
	v_sub_f32_e32 v32, v60, v55
	v_exp_f32_e32 v32, v32
	s_nop 0
	v_add_f32_e32 v33, v32, v33
	v_pk_fma_f32 v[28:29], v[36:37], v[32:33], v[28:29] op_sel_hi:[1,0,1]
	v_pk_fma_f32 v[30:31], v[38:39], v[32:33], v[30:31] op_sel_hi:[1,0,1]
	v_sub_f32_e32 v32, v56, v55
	v_exp_f32_e32 v32, v32
	s_nop 0
	v_add_f32_e32 v33, v32, v33
	v_pk_fma_f32 v[30:31], v[42:43], v[32:33], v[30:31] op_sel_hi:[1,0,1]
	v_pk_fma_f32 v[28:29], v[40:41], v[32:33], v[28:29] op_sel_hi:[1,0,1]
	v_sub_f32_e32 v32, v63, v55
	v_exp_f32_e32 v32, v32
	s_nop 0
	v_add_f32_e32 v33, v32, v33
	v_pk_fma_f32 v[28:29], v[78:79], v[32:33], v[28:29] op_sel_hi:[1,0,1]
	v_pk_fma_f32 v[30:31], v[80:81], v[32:33], v[30:31] op_sel_hi:[1,0,1]
	v_sub_f32_e32 v32, v59, v55
	v_exp_f32_e32 v32, v32
	s_nop 0
	v_add_f32_e32 v33, v32, v33
	v_pk_fma_f32 v[30:31], v[76:77], v[32:33], v[30:31] op_sel_hi:[1,0,1]
	v_pk_fma_f32 v[28:29], v[74:75], v[32:33], v[28:29] op_sel_hi:[1,0,1]
	v_sub_f32_e32 v32, v54, v55
	v_exp_f32_e32 v32, v32
	s_nop 0
	v_add_f32_e32 v33, v32, v33
	v_pk_fma_f32 v[28:29], v[82:83], v[32:33], v[28:29] op_sel_hi:[1,0,1]
	v_pk_fma_f32 v[30:31], v[84:85], v[32:33], v[30:31] op_sel_hi:[1,0,1]
	v_sub_f32_e32 v32, v52, v55
	v_exp_f32_e32 v32, v32
	s_nop 0
	v_add_f32_e32 v33, v32, v33
	v_pk_fma_f32 v[30:31], v[88:89], v[32:33], v[30:31] op_sel_hi:[1,0,1]
	v_pk_fma_f32 v[28:29], v[86:87], v[32:33], v[28:29] op_sel_hi:[1,0,1]
	v_sub_f32_e32 v32, v73, v55
	v_exp_f32_e32 v32, v32
	s_nop 0
	v_add_f32_e32 v33, v32, v33
	v_pk_fma_f32 v[24:25], v[24:25], v[32:33], v[28:29] op_sel_hi:[1,0,1]
	v_sub_f32_e32 v28, v72, v55
	v_exp_f32_e32 v28, v28
	v_pk_fma_f32 v[26:27], v[26:27], v[32:33], v[30:31] op_sel_hi:[1,0,1]
	v_add_f32_e32 v29, v28, v33
	v_pk_fma_f32 v[20:21], v[20:21], v[28:29], v[24:25] op_sel_hi:[1,0,1]
	v_sub_f32_e32 v24, v70, v55
	v_exp_f32_e32 v24, v24
	v_pk_fma_f32 v[22:23], v[22:23], v[28:29], v[26:27] op_sel_hi:[1,0,1]
	v_add_f32_e32 v25, v24, v29
	v_pk_fma_f32 v[16:17], v[16:17], v[24:25], v[20:21] op_sel_hi:[1,0,1]
	v_sub_f32_e32 v20, v71, v55
	v_exp_f32_e32 v20, v20
	v_pk_fma_f32 v[18:19], v[18:19], v[24:25], v[22:23] op_sel_hi:[1,0,1]
	v_add_f32_e32 v21, v20, v25
	v_pk_fma_f32 v[12:13], v[12:13], v[20:21], v[16:17] op_sel_hi:[1,0,1]
	v_sub_f32_e32 v16, v67, v55
	v_exp_f32_e32 v16, v16
	v_pk_fma_f32 v[14:15], v[14:15], v[20:21], v[18:19] op_sel_hi:[1,0,1]
	v_add_f32_e32 v17, v16, v21
	v_pk_fma_f32 v[8:9], v[8:9], v[16:17], v[12:13] op_sel_hi:[1,0,1]
	v_sub_f32_e32 v12, v65, v55
	v_exp_f32_e32 v12, v12
	v_pk_fma_f32 v[10:11], v[10:11], v[16:17], v[14:15] op_sel_hi:[1,0,1]
	v_add_f32_e32 v13, v12, v17
	s_waitcnt vmcnt(0)
	v_pk_fma_f32 v[10:11], v[6:7], v[12:13], v[10:11] op_sel_hi:[1,0,1]
	v_pk_fma_f32 v[4:5], v[4:5], v[12:13], v[8:9] op_sel_hi:[1,0,1]
	ds_bpermute_b32 v12, v118, v13
	ds_bpermute_b32 v6, v118, v4
	ds_bpermute_b32 v7, v118, v5
	ds_bpermute_b32 v8, v118, v10
	ds_bpermute_b32 v9, v118, v11
	s_waitcnt lgkmcnt(4)
	v_add_f32_e32 v12, v13, v12
	ds_bpermute_b32 v13, v119, v12
	s_waitcnt lgkmcnt(3)
	v_pk_add_f32 v[4:5], v[4:5], v[6:7]
	ds_bpermute_b32 v6, v119, v4
	s_waitcnt lgkmcnt(2)
	v_pk_add_f32 v[8:9], v[10:11], v[8:9]
	ds_bpermute_b32 v7, v119, v5
	ds_bpermute_b32 v10, v119, v8
	ds_bpermute_b32 v11, v119, v9
	s_and_saveexec_b64 s[30:31], s[38:39]
	s_cbranch_execz .LBB0_531
	global_load_dwordx2 v[14:15], v2, s[22:23] offset:2048
	s_waitcnt lgkmcnt(2)
	v_pk_add_f32 v[4:5], v[4:5], v[6:7]
	s_waitcnt lgkmcnt(0)
	v_pk_add_f32 v[6:7], v[8:9], v[10:11]
	v_sub_f32_e32 v8, v53, v55
	v_sub_f32_e32 v9, v120, v55
	v_exp_f32_e32 v8, v8
	v_exp_f32_e32 v9, v9
	v_add_f32_e32 v12, v12, v13
	s_lshl_b32 s21, s41, 6
	v_lshlrev_b32_e32 v18, 16, v107
	v_and_b32_e32 v19, 0xffff0000, v107
	s_mul_hi_i32 s22, s20, 0xc00
	s_mulk_i32 s20, 0xc00
	v_add_f32_e32 v10, v8, v12
	s_add_u32 s20, s34, s20
	v_pk_fma_f32 v[6:7], v[8:9], v[18:19], v[6:7] op_sel_hi:[0,1,1]
	v_add_f32_e32 v9, v9, v10
	s_addc_u32 s24, s35, s22
	v_div_scale_f32 v10, s[22:23], v9, v9, 1.0
	v_rcp_f32_e32 v11, v10
	v_lshlrev_b32_e32 v16, 16, v106
	v_and_b32_e32 v17, 0xffff0000, v106
	v_pk_fma_f32 v[4:5], v[8:9], v[16:17], v[4:5] op_sel_hi:[0,1,1]
	v_fma_f32 v12, -v10, v11, 1.0
	v_div_scale_f32 v8, vcc, 1.0, v9, 1.0
	v_fmac_f32_e32 v11, v12, v11
	v_mul_f32_e32 v12, v8, v11
	v_fma_f32 v13, -v10, v12, v8
	v_fmac_f32_e32 v12, v13, v11
	v_fma_f32 v8, -v10, v12, v8
	v_div_fmas_f32 v8, v8, v11, v12
	v_div_fixup_f32 v8, v8, v9, 1.0
	s_lshl_b32 s21, s21, 1
	v_mul_f32_e32 v4, v8, v4
	v_mul_f32_e32 v5, v8, v5
	v_mul_f32_e32 v6, v8, v6
	v_mul_f32_e32 v7, v8, v7
	s_add_u32 s20, s20, s21
	s_addc_u32 s21, s24, 0
	s_waitcnt vmcnt(0)
	v_lshlrev_b32_e32 v8, 16, v14
	v_and_b32_e32 v9, 0xffff0000, v14
	v_lshlrev_b32_e32 v10, 16, v15
	v_and_b32_e32 v11, 0xffff0000, v15
	v_mul_f32_e32 v4, v4, v8
	v_mul_f32_e32 v5, v5, v9
	v_mul_f32_e32 v6, v6, v10
	v_mul_f32_e32 v7, v7, v11
	v_cvt_pk_bf16_f32 v4, v4, v5
	v_cvt_pk_bf16_f32 v5, v6, v7
	global_store_dwordx2 v2, v[4:5], s[20:21] sc1
	s_branch .LBB0_531

.Lmy_sc_aa:
	s_or_b64 exec, exec, s[44:45]
	v_readlane_b32 s44, v254, 33
	v_readlane_b32 s45, v254, 34
	v_and_b32_e32 v145, 63, v132
	s_nop 0
	v_lshl_add_u64 v[136:137], s[44:45], 0, v[80:81]
	s_waitcnt lgkmcnt(0)
	v_lshl_add_u64 v[4:5], v[136:137], 2, s[40:41]
	v_lshl_add_u64 v[4:5], v[4:5], 0, v[2:3]
	v_add_co_u32_e32 v6, vcc, 0x1000, v4
	s_nop 1
	v_addc_co_u32_e32 v7, vcc, 0, v5, vcc
	global_load_dwordx4 v[80:83], v[4:5], off nt
	global_load_dwordx4 v[76:79], v[6:7], off nt
	v_add_co_u32_e32 v6, vcc, s91, v4
	s_nop 1
	v_addc_co_u32_e32 v7, vcc, 0, v5, vcc
	v_add_co_u32_e32 v8, vcc, 0x3000, v4
	s_nop 1
	v_addc_co_u32_e32 v9, vcc, 0, v5, vcc
	global_load_dwordx4 v[72:75], v[6:7], off nt
	global_load_dwordx4 v[68:71], v[8:9], off nt
	v_add_co_u32_e32 v6, vcc, s90, v4
	s_nop 1
	v_addc_co_u32_e32 v7, vcc, 0, v5, vcc
	v_add_co_u32_e32 v8, vcc, 0x5000, v4
	s_nop 1
	v_addc_co_u32_e32 v9, vcc, 0, v5, vcc
	global_load_dwordx4 v[60:63], v[6:7], off nt
	global_load_dwordx4 v[52:55], v[8:9], off nt
	v_add_co_u32_e32 v6, vcc, s33, v4
	s_nop 1
	v_addc_co_u32_e32 v7, vcc, 0, v5, vcc
	v_add_co_u32_e32 v8, vcc, 0x7000, v4
	s_nop 1
	v_addc_co_u32_e32 v9, vcc, 0, v5, vcc
	global_load_dwordx4 v[48:51], v[6:7], off nt
	global_load_dwordx4 v[40:43], v[8:9], off nt
	v_add_co_u32_e32 v6, vcc, s92, v4
	s_nop 1
	v_addc_co_u32_e32 v7, vcc, 0, v5, vcc
	v_add_co_u32_e32 v8, vcc, 0x9000, v4
	s_nop 1
	v_addc_co_u32_e32 v9, vcc, 0, v5, vcc
	global_load_dwordx4 v[36:39], v[6:7], off nt
	global_load_dwordx4 v[28:31], v[8:9], off nt
	v_add_co_u32_e32 v6, vcc, s93, v4
	s_nop 1
	v_addc_co_u32_e32 v7, vcc, 0, v5, vcc
	v_add_co_u32_e32 v8, vcc, 0xb000, v4
	s_nop 1
	v_addc_co_u32_e32 v9, vcc, 0, v5, vcc
	global_load_dwordx4 v[24:27], v[6:7], off nt
	global_load_dwordx4 v[20:23], v[8:9], off nt
	v_add_co_u32_e32 v6, vcc, s6, v4
	s_nop 1
	v_addc_co_u32_e32 v7, vcc, 0, v5, vcc
	v_add_co_u32_e32 v8, vcc, 0xd000, v4
	s_nop 1
	v_addc_co_u32_e32 v9, vcc, 0, v5, vcc
	global_load_dwordx4 v[16:19], v[6:7], off nt
	global_load_dwordx4 v[12:15], v[8:9], off nt
	v_add_co_u32_e32 v6, vcc, s95, v4
	s_nop 1
	v_addc_co_u32_e32 v7, vcc, 0, v5, vcc
	v_add_co_u32_e32 v4, vcc, 0xf000, v4
	s_nop 1
	v_addc_co_u32_e32 v5, vcc, 0, v5, vcc
	global_load_dwordx4 v[8:11], v[6:7], off nt
	s_nop 0
	global_load_dwordx4 v[4:7], v[4:5], off nt
	v_lshl_add_u32 v146, v145, 2, 0
	s_barrier
	ds_read2st64_b32 v[148:149], v146 offset1:1
	ds_read2st64_b32 v[150:151], v146 offset0:2 offset1:3
	v_cmp_lt_i32_e32 vcc, v236, v235
	v_readlane_b32 s1, v254, 31
	s_waitcnt lgkmcnt(0)
	v_max_f32_e32 v138, v151, v151
	v_max_f32_e32 v147, v150, v150
	v_max_f32_e32 v138, v147, v138
	v_max3_f32 v138, v148, v149, v138
	s_nop 1
	v_max_f32_dpp v138, v138, v138 quad_perm:[1,0,3,2] row_mask:0xf bank_mask:0xf
	s_nop 1
	v_max_f32_dpp v138, v138, v138 quad_perm:[2,3,0,1] row_mask:0xf bank_mask:0xf
	s_nop 1
	v_max_f32_dpp v138, v138, v138 row_half_mirror row_mask:0xf bank_mask:0xf
	s_nop 1
	v_max_f32_dpp v138, v138, v138 row_mirror row_mask:0xf bank_mask:0xf
	s_nop 1
	ds_bpermute_b32 v147, v144, v138
	s_waitcnt lgkmcnt(0)
	v_max_f32_e32 v147, v147, v147
	v_max_f32_e32 v147, v138, v147
	v_cndmask_b32_e32 v138, v231, v236, vcc
	v_lshlrev_b32_e32 v138, 2, v138
	ds_bpermute_b32 v152, v138, v147
	s_waitcnt lgkmcnt(0)
	v_max_f32_e32 v152, v152, v152
	v_max_f32_e32 v147, v147, v152
	v_sub_f32_e32 v149, v149, v147
	v_sub_f32_e32 v148, v148, v147
	v_exp_f32_e32 v152, v149
	v_sub_f32_e32 v149, v150, v147
	v_sub_f32_e32 v150, v151, v147
	v_exp_f32_e32 v148, v148
	v_exp_f32_e32 v149, v149
	v_exp_f32_e32 v153, v150
	s_nop 0
	v_pk_add_f32 v[148:149], v[148:149], v[152:153]
	s_nop 0
	v_add_f32_e32 v148, v148, v149
	s_nop 1
	v_add_f32_dpp v148, v148, v148 quad_perm:[1,0,3,2] row_mask:0xf bank_mask:0xf
	s_nop 1
	v_add_f32_dpp v148, v148, v148 quad_perm:[2,3,0,1] row_mask:0xf bank_mask:0xf
	s_nop 1
	v_add_f32_dpp v148, v148, v148 row_half_mirror row_mask:0xf bank_mask:0xf
	s_nop 1
	v_add_f32_dpp v148, v148, v148 row_mirror row_mask:0xf bank_mask:0xf
	s_nop 1
	ds_bpermute_b32 v149, v144, v148
	s_waitcnt lgkmcnt(0)
	v_add_f32_e32 v148, v148, v149
	ds_bpermute_b32 v149, v138, v148
	s_waitcnt lgkmcnt(0)
	v_add_f32_e32 v148, v148, v149
	v_div_scale_f32 v149, s[40:41], v148, v148, 1.0
	v_rcp_f32_e32 v150, v149
	v_cmp_gt_u32_e64 s[40:41], 32, v145
	v_lshl_add_u32 v145, v133, 4, s1
	v_fma_f32 v151, -v149, v150, 1.0
	v_fmac_f32_e32 v150, v151, v150
	v_div_scale_f32 v151, vcc, 1.0, v148, 1.0
	v_mul_f32_e32 v152, v151, v150
	v_fma_f32 v153, -v149, v152, v151
	v_fmac_f32_e32 v152, v153, v150
	v_fma_f32 v149, -v149, v152, v151
	v_div_fmas_f32 v149, v149, v150, v152
	ds_read2_b32 v[150:151], v139 offset1:2
	ds_read2_b32 v[152:153], v139 offset0:4 offset1:6
	ds_read2_b32 v[154:155], v139 offset0:8 offset1:10
	ds_read2_b32 v[156:157], v139 offset0:12 offset1:14
	v_div_fixup_f32 v148, v149, v148, 1.0
	s_waitcnt lgkmcnt(3)
	v_sub_f32_e32 v149, v150, v147
	v_exp_f32_e32 v149, v149
	s_nop 0
	v_mul_f32_e32 v150, v149, v148
	v_sub_f32_e32 v149, v151, v147
	v_exp_f32_e32 v149, v149
	s_waitcnt vmcnt(17)
	v_pk_fma_f32 v[128:129], v[128:129], v[150:151], 0 op_sel_hi:[1,0,0]
	v_pk_fma_f32 v[130:131], v[130:131], v[150:151], 0 op_sel_hi:[1,0,0]
	v_mul_f32_e32 v150, v149, v148
	v_pk_fma_f32 v[124:125], v[124:125], v[150:151], v[128:129] op_sel_hi:[1,0,1]
	s_waitcnt lgkmcnt(2)
	v_sub_f32_e32 v128, v152, v147
	v_exp_f32_e32 v128, v128
	v_pk_fma_f32 v[126:127], v[126:127], v[150:151], v[130:131] op_sel_hi:[1,0,1]
	v_mul_f32_e32 v128, v128, v148
	v_pk_fma_f32 v[116:117], v[116:117], v[128:129], v[124:125] op_sel_hi:[1,0,1]
	v_sub_f32_e32 v124, v153, v147
	v_exp_f32_e32 v124, v124
	v_pk_fma_f32 v[118:119], v[118:119], v[128:129], v[126:127] op_sel_hi:[1,0,1]
	v_mul_f32_e32 v124, v124, v148
	v_pk_fma_f32 v[116:117], v[120:121], v[124:125], v[116:117] op_sel_hi:[1,0,1]
	s_waitcnt lgkmcnt(1)
	v_sub_f32_e32 v120, v154, v147
	v_exp_f32_e32 v120, v120
	v_pk_fma_f32 v[118:119], v[122:123], v[124:125], v[118:119] op_sel_hi:[1,0,1]
	v_mul_f32_e32 v120, v148, v120
	v_pk_fma_f32 v[108:109], v[108:109], v[120:121], v[116:117] op_sel_hi:[1,0,1]
	v_sub_f32_e32 v116, v155, v147
	v_exp_f32_e32 v116, v116
	v_pk_fma_f32 v[110:111], v[110:111], v[120:121], v[118:119] op_sel_hi:[1,0,1]
	v_mul_f32_e32 v116, v148, v116
	v_pk_fma_f32 v[108:109], v[112:113], v[116:117], v[108:109] op_sel_hi:[1,0,1]
	s_waitcnt lgkmcnt(0)
	v_sub_f32_e32 v112, v156, v147
	v_exp_f32_e32 v112, v112
	v_pk_fma_f32 v[110:111], v[114:115], v[116:117], v[110:111] op_sel_hi:[1,0,1]
	v_mul_f32_e32 v112, v148, v112
	v_pk_fma_f32 v[100:101], v[100:101], v[112:113], v[108:109] op_sel_hi:[1,0,1]
	v_sub_f32_e32 v108, v157, v147
	v_exp_f32_e32 v108, v108
	v_pk_fma_f32 v[102:103], v[102:103], v[112:113], v[110:111] op_sel_hi:[1,0,1]
	v_mul_f32_e32 v108, v148, v108
	v_pk_fma_f32 v[100:101], v[104:105], v[108:109], v[100:101] op_sel_hi:[1,0,1]
	ds_read2_b32 v[104:105], v139 offset0:16 offset1:18
	v_pk_fma_f32 v[102:103], v[106:107], v[108:109], v[102:103] op_sel_hi:[1,0,1]
	s_waitcnt lgkmcnt(0)
	v_sub_f32_e32 v104, v104, v147
	v_exp_f32_e32 v104, v104
	s_nop 0
	v_mul_f32_e32 v104, v148, v104
	v_pk_fma_f32 v[100:101], v[92:93], v[104:105], v[100:101] op_sel_hi:[1,0,1]
	v_pk_fma_f32 v[92:93], v[94:95], v[104:105], v[102:103] op_sel_hi:[1,0,1]
	v_sub_f32_e32 v94, v105, v147
	v_exp_f32_e32 v94, v94
	s_nop 0
	v_mul_f32_e32 v94, v148, v94
	v_pk_fma_f32 v[92:93], v[98:99], v[94:95], v[92:93] op_sel_hi:[1,0,1]
	v_pk_fma_f32 v[94:95], v[96:97], v[94:95], v[100:101] op_sel_hi:[1,0,1]
	ds_read2_b32 v[96:97], v139 offset0:20 offset1:22
	s_waitcnt lgkmcnt(0)
	v_sub_f32_e32 v96, v96, v147
	v_exp_f32_e32 v96, v96
	s_nop 0
	v_mul_f32_e32 v96, v148, v96
	v_pk_fma_f32 v[86:87], v[86:87], v[96:97], v[92:93] op_sel_hi:[1,0,1]
	v_sub_f32_e32 v92, v97, v147
	v_exp_f32_e32 v92, v92
	v_pk_fma_f32 v[84:85], v[84:85], v[96:97], v[94:95] op_sel_hi:[1,0,1]
	v_mul_f32_e32 v92, v148, v92
	v_pk_fma_f32 v[84:85], v[88:89], v[92:93], v[84:85] op_sel_hi:[1,0,1]
	ds_read2_b32 v[88:89], v139 offset0:24 offset1:26
	v_pk_fma_f32 v[86:87], v[90:91], v[92:93], v[86:87] op_sel_hi:[1,0,1]
	s_waitcnt lgkmcnt(0)
	v_sub_f32_e32 v88, v88, v147
	v_exp_f32_e32 v88, v88
	s_nop 0
	v_mul_f32_e32 v88, v148, v88
	v_pk_fma_f32 v[64:65], v[64:65], v[88:89], v[84:85] op_sel_hi:[1,0,1]
	v_sub_f32_e32 v84, v89, v147
	v_exp_f32_e32 v84, v84
	v_pk_fma_f32 v[66:67], v[66:67], v[88:89], v[86:87] op_sel_hi:[1,0,1]
	v_mul_f32_e32 v84, v148, v84
	v_pk_fma_f32 v[56:57], v[56:57], v[84:85], v[64:65] op_sel_hi:[1,0,1]
	ds_read2_b32 v[64:65], v139 offset0:28 offset1:30
	v_pk_fma_f32 v[58:59], v[58:59], v[84:85], v[66:67] op_sel_hi:[1,0,1]
	s_waitcnt lgkmcnt(0)
	v_sub_f32_e32 v64, v64, v147
	v_exp_f32_e32 v64, v64
	s_nop 0
	v_mul_f32_e32 v64, v148, v64
	v_pk_fma_f32 v[56:57], v[44:45], v[64:65], v[56:57] op_sel_hi:[1,0,1]
	v_pk_fma_f32 v[44:45], v[46:47], v[64:65], v[58:59] op_sel_hi:[1,0,1]
	v_sub_f32_e32 v46, v65, v147
	v_exp_f32_e32 v46, v46
	s_nop 0
	v_mul_f32_e32 v46, v148, v46
	s_waitcnt vmcnt(16)
	v_pk_fma_f32 v[44:45], v[34:35], v[46:47], v[44:45] op_sel_hi:[1,0,1]
	v_pk_fma_f32 v[32:33], v[32:33], v[46:47], v[56:57] op_sel_hi:[1,0,1]
	ds_bpermute_b32 v34, v138, v32
	ds_bpermute_b32 v35, v138, v33
	ds_bpermute_b32 v46, v138, v44
	ds_bpermute_b32 v47, v138, v45
	s_and_saveexec_b64 s[44:45], s[40:41]
	s_cbranch_execz .LBB0_590
	s_waitcnt lgkmcnt(0)
	v_pk_add_f32 v[46:47], v[44:45], v[46:47]
	v_pk_add_f32 v[44:45], v[32:33], v[34:35]
	ds_write_b128 v145, v[44:47] offset:2048

.Lmy_sc_ab:
	s_or_b64 exec, exec, s[44:45]
	s_waitcnt lgkmcnt(0)
	s_barrier
	ds_read2st64_b32 v[4:5], v146 offset0:4 offset1:5
	ds_read2st64_b32 v[6:7], v146 offset0:6 offset1:7
	v_add_u32_e32 v12, 0x400, v139
	s_waitcnt lgkmcnt(0)
	v_max_f32_e32 v8, v7, v7
	v_max_f32_e32 v9, v6, v6
	v_max_f32_e32 v8, v9, v8
	v_max3_f32 v8, v4, v5, v8
	s_nop 1
	v_max_f32_dpp v8, v8, v8 quad_perm:[1,0,3,2] row_mask:0xf bank_mask:0xf
	s_nop 1
	v_max_f32_dpp v8, v8, v8 quad_perm:[2,3,0,1] row_mask:0xf bank_mask:0xf
	s_nop 1
	v_max_f32_dpp v8, v8, v8 row_half_mirror row_mask:0xf bank_mask:0xf
	s_nop 1
	v_max_f32_dpp v8, v8, v8 row_mirror row_mask:0xf bank_mask:0xf
	s_nop 1
	ds_bpermute_b32 v9, v144, v8
	s_waitcnt lgkmcnt(0)
	v_max_f32_e32 v9, v9, v9
	v_max_f32_e32 v8, v8, v9
	ds_bpermute_b32 v9, v138, v8
	s_waitcnt lgkmcnt(0)
	v_max_f32_e32 v9, v9, v9
	v_max_f32_e32 v10, v8, v9
	v_sub_f32_e32 v5, v5, v10
	v_sub_f32_e32 v4, v4, v10
	v_exp_f32_e32 v8, v5
	v_sub_f32_e32 v5, v6, v10
	v_sub_f32_e32 v6, v7, v10
	v_exp_f32_e32 v4, v4
	v_exp_f32_e32 v5, v5
	v_exp_f32_e32 v9, v6
	s_nop 0
	v_pk_add_f32 v[4:5], v[4:5], v[8:9]
	s_nop 0
	v_add_f32_e32 v4, v4, v5
	s_nop 1
	v_add_f32_dpp v4, v4, v4 quad_perm:[1,0,3,2] row_mask:0xf bank_mask:0xf
	s_nop 1
	v_add_f32_dpp v4, v4, v4 quad_perm:[2,3,0,1] row_mask:0xf bank_mask:0xf
	s_nop 1
	v_add_f32_dpp v4, v4, v4 row_half_mirror row_mask:0xf bank_mask:0xf
	s_nop 1
	v_add_f32_dpp v4, v4, v4 row_mirror row_mask:0xf bank_mask:0xf
	s_nop 1
	ds_bpermute_b32 v5, v144, v4
	s_waitcnt lgkmcnt(0)
	v_add_f32_e32 v4, v4, v5
	ds_bpermute_b32 v5, v138, v4
	s_waitcnt lgkmcnt(0)
	v_add_f32_e32 v4, v4, v5
	v_div_scale_f32 v5, s[38:39], v4, v4, 1.0
	v_rcp_f32_e32 v6, v5
	s_nop 0
	v_fma_f32 v7, -v5, v6, 1.0
	v_fmac_f32_e32 v6, v7, v6
	v_div_scale_f32 v7, vcc, 1.0, v4, 1.0
	v_mul_f32_e32 v8, v7, v6
	v_fma_f32 v9, -v5, v8, v7
	v_fmac_f32_e32 v8, v9, v6
	v_fma_f32 v5, -v5, v8, v7
	v_div_fmas_f32 v5, v5, v6, v8
	v_div_fixup_f32 v11, v5, v4, 1.0
	ds_read2_b32 v[4:5], v12 offset1:2
	ds_read2_b32 v[6:7], v12 offset0:4 offset1:6
	ds_read2_b32 v[8:9], v12 offset0:8 offset1:10
	ds_read2_b32 v[14:15], v12 offset0:12 offset1:14
	s_waitcnt lgkmcnt(3)
	v_sub_f32_e32 v4, v4, v10
	v_exp_f32_e32 v4, v4
	s_waitcnt lgkmcnt(2)
	v_sub_f32_e32 v6, v6, v10
	v_exp_f32_e32 v6, v6
	v_mul_f32_e32 v4, v4, v11
	s_waitcnt vmcnt(15)
	v_pk_fma_f32 v[16:17], v[104:105], v[4:5], 0 op_sel_hi:[1,0,0]
	v_pk_fma_f32 v[18:19], v[106:107], v[4:5], 0 op_sel_hi:[1,0,0]
	v_sub_f32_e32 v4, v5, v10
	v_exp_f32_e32 v4, v4
	v_mul_f32_e32 v6, v6, v11
	v_mul_f32_e32 v4, v4, v11
	s_waitcnt vmcnt(14)
	v_pk_fma_f32 v[18:19], v[102:103], v[4:5], v[18:19] op_sel_hi:[1,0,1]
	v_pk_fma_f32 v[4:5], v[100:101], v[4:5], v[16:17] op_sel_hi:[1,0,1]
	s_waitcnt vmcnt(13)
	v_pk_fma_f32 v[16:17], v[114:115], v[6:7], v[18:19] op_sel_hi:[1,0,1]
	v_pk_fma_f32 v[4:5], v[112:113], v[6:7], v[4:5] op_sel_hi:[1,0,1]
	v_sub_f32_e32 v6, v7, v10
	v_exp_f32_e32 v6, v6
	s_nop 0
	v_mul_f32_e32 v6, v6, v11
	s_waitcnt vmcnt(12)
	v_pk_fma_f32 v[16:17], v[110:111], v[6:7], v[16:17] op_sel_hi:[1,0,1]
	v_pk_fma_f32 v[4:5], v[108:109], v[6:7], v[4:5] op_sel_hi:[1,0,1]
	s_waitcnt lgkmcnt(1)
	v_sub_f32_e32 v6, v8, v10
	v_exp_f32_e32 v6, v6
	v_sub_f32_e32 v8, v9, v10
	v_exp_f32_e32 v8, v8
	v_mul_f32_e32 v6, v11, v6
	s_waitcnt vmcnt(11)
	v_pk_fma_f32 v[4:5], v[120:121], v[6:7], v[4:5] op_sel_hi:[1,0,1]
	v_pk_fma_f32 v[6:7], v[122:123], v[6:7], v[16:17] op_sel_hi:[1,0,1]
	v_mul_f32_e32 v8, v11, v8
	s_waitcnt vmcnt(10)
	v_pk_fma_f32 v[6:7], v[118:119], v[8:9], v[6:7] op_sel_hi:[1,0,1]
	v_pk_fma_f32 v[4:5], v[116:117], v[8:9], v[4:5] op_sel_hi:[1,0,1]
	s_waitcnt lgkmcnt(0)
	v_sub_f32_e32 v8, v14, v10
	v_exp_f32_e32 v8, v8
	s_nop 0
	v_mul_f32_e32 v8, v11, v8
	s_waitcnt vmcnt(9)
	v_pk_fma_f32 v[4:5], v[128:129], v[8:9], v[4:5] op_sel_hi:[1,0,1]
	v_pk_fma_f32 v[6:7], v[130:131], v[8:9], v[6:7] op_sel_hi:[1,0,1]
	v_sub_f32_e32 v8, v15, v10
	v_exp_f32_e32 v8, v8
	s_nop 0
	v_mul_f32_e32 v8, v11, v8
	s_waitcnt vmcnt(8)
	v_pk_fma_f32 v[6:7], v[126:127], v[8:9], v[6:7] op_sel_hi:[1,0,1]
	v_pk_fma_f32 v[4:5], v[124:125], v[8:9], v[4:5] op_sel_hi:[1,0,1]
	ds_read2_b32 v[8:9], v12 offset0:16 offset1:18
	s_waitcnt lgkmcnt(0)
	v_sub_f32_e32 v8, v8, v10
	v_exp_f32_e32 v8, v8
	s_nop 0
	v_mul_f32_e32 v8, v11, v8
	s_waitcnt vmcnt(7)
	v_pk_fma_f32 v[14:15], v[96:97], v[8:9], v[4:5] op_sel_hi:[1,0,1]
	v_pk_fma_f32 v[4:5], v[98:99], v[8:9], v[6:7] op_sel_hi:[1,0,1]
	v_sub_f32_e32 v6, v9, v10
	ds_read2_b32 v[8:9], v12 offset0:20 offset1:22
	v_exp_f32_e32 v6, v6
	s_waitcnt lgkmcnt(0)
	v_sub_f32_e32 v8, v8, v10
	v_exp_f32_e32 v8, v8
	v_mul_f32_e32 v6, v11, v6
	s_waitcnt vmcnt(6)
	v_pk_fma_f32 v[4:5], v[94:95], v[6:7], v[4:5] op_sel_hi:[1,0,1]
	v_pk_fma_f32 v[6:7], v[92:93], v[6:7], v[14:15] op_sel_hi:[1,0,1]
	v_mul_f32_e32 v8, v11, v8
	s_waitcnt vmcnt(5)
	v_pk_fma_f32 v[6:7], v[88:89], v[8:9], v[6:7] op_sel_hi:[1,0,1]
	v_pk_fma_f32 v[4:5], v[90:91], v[8:9], v[4:5] op_sel_hi:[1,0,1]
	v_sub_f32_e32 v8, v9, v10
	v_exp_f32_e32 v8, v8
	s_nop 0
	v_mul_f32_e32 v8, v11, v8
	s_waitcnt vmcnt(4)
	v_pk_fma_f32 v[4:5], v[86:87], v[8:9], v[4:5] op_sel_hi:[1,0,1]
	v_pk_fma_f32 v[6:7], v[84:85], v[8:9], v[6:7] op_sel_hi:[1,0,1]
	ds_read2_b32 v[8:9], v12 offset0:24 offset1:26
	s_waitcnt lgkmcnt(0)
	v_sub_f32_e32 v8, v8, v10
	v_exp_f32_e32 v8, v8
	s_nop 0
	v_mul_f32_e32 v8, v11, v8
	s_waitcnt vmcnt(3)
	v_pk_fma_f32 v[6:7], v[64:65], v[8:9], v[6:7] op_sel_hi:[1,0,1]
	v_pk_fma_f32 v[4:5], v[66:67], v[8:9], v[4:5] op_sel_hi:[1,0,1]
	v_sub_f32_e32 v8, v9, v10
	v_exp_f32_e32 v8, v8
	s_nop 0
	v_mul_f32_e32 v8, v11, v8
	s_waitcnt vmcnt(2)
	v_pk_fma_f32 v[4:5], v[58:59], v[8:9], v[4:5] op_sel_hi:[1,0,1]
	v_pk_fma_f32 v[6:7], v[56:57], v[8:9], v[6:7] op_sel_hi:[1,0,1]
	ds_read2_b32 v[8:9], v12 offset0:28 offset1:30
	s_waitcnt lgkmcnt(0)
	v_sub_f32_e32 v8, v8, v10
	v_exp_f32_e32 v8, v8
	s_nop 0
	v_mul_f32_e32 v8, v11, v8
	s_waitcnt vmcnt(1)
	v_pk_fma_f32 v[6:7], v[44:45], v[8:9], v[6:7] op_sel_hi:[1,0,1]
	v_pk_fma_f32 v[4:5], v[46:47], v[8:9], v[4:5] op_sel_hi:[1,0,1]
	v_sub_f32_e32 v8, v9, v10
	v_exp_f32_e32 v8, v8
	s_nop 0
	v_mul_f32_e32 v10, v11, v8
	s_waitcnt vmcnt(0)
	v_pk_fma_f32 v[8:9], v[34:35], v[10:11], v[4:5] op_sel_hi:[1,0,1]
	v_pk_fma_f32 v[4:5], v[32:33], v[10:11], v[6:7] op_sel_hi:[1,0,1]
	ds_bpermute_b32 v6, v138, v4
	ds_bpermute_b32 v7, v138, v5
	ds_bpermute_b32 v10, v138, v8
	ds_bpermute_b32 v11, v138, v9
	s_and_saveexec_b64 s[38:39], s[40:41]
	s_cbranch_execz .LBB0_626
	s_waitcnt lgkmcnt(0)
	v_pk_add_f32 v[8:9], v[8:9], v[10:11]
	v_pk_add_f32 v[6:7], v[4:5], v[6:7]
	ds_write_b128 v145, v[6:9] offset:2048

.LBB0_631:
	s_ashr_i32 s1, s80, 4
	s_add_i32 s20, s1, 0x4000
	s_and_b32 s0, s80, 15
	s_ashr_i32 s21, s20, 31
	s_mul_i32 s14, s20, 0x1800
	s_mul_hi_i32 s4, s20, 0x1800
	s_add_u32 s14, s72, s14
	s_addc_u32 s4, s73, s4
	s_lshl_b32 s22, s0, 7
	s_add_u32 s22, s14, s22
	s_addc_u32 s23, s4, 0
	s_lshl_b64 s[28:29], s[20:21], 8
	s_add_u32 s4, s34, s28
	s_addc_u32 s14, s35, s29
	s_lshl_b32 s21, s80, 3
	s_and_b32 s21, s21, 64
	s_lshl_b32 s24, s21, 1
	s_add_u32 s30, s4, s24
	s_addc_u32 s31, s14, 0
	s_add_u32 s4, s78, s28
	s_addc_u32 s14, s79, s29
	s_add_u32 s28, s4, s24
	s_waitcnt vmcnt(24) lgkmcnt(2)
	v_lshl_add_u64 v[6:7], s[30:31], 0, v[104:105]
	s_addc_u32 s29, s14, 0
	v_lshl_add_u64 v[4:5], s[22:23], 0, v[104:105]
	global_load_dwordx2 v[6:7], v[6:7], off
	s_nop 0
	global_load_dwordx2 v[106:107], v2, s[28:29]
	global_load_dwordx2 v[112:113], v[4:5], off
	s_or_b32 s28, s0, s74
	s_ashr_i32 s29, s28, 31
	s_lshl_b64 s[28:29], s[28:29], 2
	s_add_u32 s28, s2, s28
	s_addc_u32 s29, s3, s29
	global_load_dword v120, v3, s[28:29]
	v_lshl_or_b32 v4, s1, 7, v197
	v_ashrrev_i32_e32 v5, 31, v4
	v_lshlrev_b64 v[110:111], 9, v[4:5]
	v_lshl_or_b32 v110, s21, 2, v110
	v_lshl_add_u64 v[4:5], v[100:101], 0, v[110:111]
	s_waitcnt vmcnt(3)
	v_lshlrev_b32_e32 v121, 16, v6
	v_and_b32_e32 v123, 0xffff0000, v6
	v_lshlrev_b32_e32 v122, 16, v7
	v_and_b32_e32 v124, 0xffff0000, v7
	v_add_co_u32_e32 v6, vcc, s17, v4
	global_load_dwordx4 v[126:129], v[4:5], off
	global_load_dwordx4 v[130:133], v[4:5], off offset:2048
	v_addc_co_u32_e32 v7, vcc, 0, v5, vcc
	v_add_co_u32_e32 v108, vcc, s91, v4
	s_movk_i32 s1, 0x6000
	s_nop 0
	v_addc_co_u32_e32 v109, vcc, 0, v5, vcc
	v_add_co_u32_e32 v8, vcc, s50, v4
	global_load_dwordx4 v[134:137], v[108:109], off
	global_load_dwordx4 v[138:141], v[108:109], off offset:2048
	v_addc_co_u32_e32 v9, vcc, 0, v5, vcc
	s_waitcnt lgkmcnt(1)
	v_add_co_u32_e32 v10, vcc, s90, v4
	s_waitcnt vmcnt(4)
	v_mul_f32_e32 v120, 0x3fb8aa3b, v120
	s_waitcnt lgkmcnt(0)
	v_addc_co_u32_e32 v11, vcc, 0, v5, vcc
	global_load_dwordx4 v[142:145], v[6:7], off offset:2048
	global_load_dwordx4 v[146:149], v[8:9], off offset:2048
	global_load_dwordx4 v[150:153], v[10:11], off offset:-4096
	global_load_dwordx4 v[96:99], v[10:11], off
	v_add_co_u32_e32 v6, vcc, s96, v4
	s_nop 1
	v_addc_co_u32_e32 v7, vcc, 0, v5, vcc
	v_add_co_u32_e32 v8, vcc, s1, v4
	s_nop 1
	v_addc_co_u32_e32 v9, vcc, 0, v5, vcc
	global_load_dwordx4 v[92:95], v[10:11], off offset:2048
	global_load_dwordx4 v[88:91], v[8:9], off offset:-4096
	global_load_dwordx4 v[80:83], v[8:9], off
	global_load_dwordx4 v[76:79], v[8:9], off offset:2048
	v_add_co_u32_e32 v8, vcc, s51, v4
	s_nop 1
	v_addc_co_u32_e32 v9, vcc, 0, v5, vcc
	v_add_co_u32_e32 v10, vcc, s92, v4
	s_nop 1
	v_addc_co_u32_e32 v11, vcc, 0, v5, vcc
	global_load_dwordx4 v[84:87], v[6:7], off offset:2048
	global_load_dwordx4 v[68:71], v[8:9], off offset:2048
	global_load_dwordx4 v[72:75], v[10:11], off offset:-4096
	global_load_dwordx4 v[64:67], v[10:11], off
	v_add_co_u32_e32 v6, vcc, s56, v4
	s_nop 1
	v_addc_co_u32_e32 v7, vcc, 0, v5, vcc
	v_add_co_u32_e32 v8, vcc, s93, v4
	s_nop 1
	v_addc_co_u32_e32 v9, vcc, 0, v5, vcc
	global_load_dwordx4 v[60:63], v[10:11], off offset:2048
	global_load_dwordx4 v[56:59], v[8:9], off offset:-4096
	global_load_dwordx4 v[48:51], v[8:9], off
	global_load_dwordx4 v[44:47], v[8:9], off offset:2048
	v_add_co_u32_e32 v8, vcc, s57, v4
	s_nop 1
	v_addc_co_u32_e32 v9, vcc, 0, v5, vcc
	v_add_co_u32_e32 v10, vcc, s6, v4
	s_nop 1
	v_addc_co_u32_e32 v11, vcc, 0, v5, vcc
	global_load_dwordx4 v[52:55], v[6:7], off offset:2048
	global_load_dwordx4 v[36:39], v[8:9], off offset:2048
	global_load_dwordx4 v[40:43], v[10:11], off offset:-4096
	global_load_dwordx4 v[32:35], v[10:11], off
	v_add_co_u32_e32 v6, vcc, s58, v4
	s_nop 1
	v_addc_co_u32_e32 v7, vcc, 0, v5, vcc
	v_add_co_u32_e32 v8, vcc, s95, v4
	s_nop 1
	v_addc_co_u32_e32 v9, vcc, 0, v5, vcc
	v_add_co_u32_e32 v4, vcc, s52, v4
	global_load_dwordx4 v[28:31], v[10:11], off offset:2048
	global_load_dwordx4 v[24:27], v[8:9], off offset:-4096
	global_load_dwordx4 v[16:19], v[8:9], off
	global_load_dwordx4 v[12:15], v[8:9], off offset:2048
	v_addc_co_u32_e32 v5, vcc, 0, v5, vcc
	global_load_dwordx4 v[20:23], v[6:7], off offset:2048
	global_load_dwordx4 v[8:11], v[4:5], off
	global_load_dwordx4 v[154:157], v[108:109], off offset:-4096
	s_nop 0
	global_load_dwordx4 v[4:7], v[4:5], off offset:2048
	v_and_b32_e32 v108, 0xffff0000, v112
	v_lshlrev_b32_e32 v109, 16, v113
	v_lshlrev_b32_e32 v112, 16, v112
	v_and_b32_e32 v113, 0xffff0000, v113
	s_waitcnt vmcnt(31)
	v_mov_b32_e32 v158, v127
	v_mov_b32_e32 v127, v129
	v_mov_b32_e32 v159, v128
	v_pk_mul_f32 v[126:127], v[126:127], v[112:113]
	s_movk_i32 s33, 0x6000
	v_pk_fma_f32 v[126:127], v[158:159], v[108:109], v[126:127]
	s_nop 0
	v_add_f32_e32 v125, v126, v127
	s_waitcnt vmcnt(30)
	v_mov_b32_e32 v126, v131
	v_mov_b32_e32 v131, v133
	v_mov_b32_e32 v127, v132
	v_pk_mul_f32 v[128:129], v[130:131], v[112:113]
	s_nop 1
	v_mov_b32_dpp v158, v125 quad_perm:[1,0,3,2] row_mask:0xf bank_mask:0xf
	v_pk_fma_f32 v[126:127], v[126:127], v[108:109], v[128:129]
	s_waitcnt lgkmcnt(0)
	v_add_f32_e32 v125, v125, v158
	v_add_f32_e32 v126, v126, v127
	s_nop 1
	v_mov_b32_dpp v127, v126 quad_perm:[1,0,3,2] row_mask:0xf bank_mask:0xf
	s_nop 1
	v_mov_b32_dpp v128, v125 quad_perm:[2,3,0,1] row_mask:0xf bank_mask:0xf
	s_waitcnt lgkmcnt(0)
	v_add_f32_e32 v126, v126, v127
	s_nop 1
	v_mov_b32_dpp v127, v126 quad_perm:[2,3,0,1] row_mask:0xf bank_mask:0xf
	s_waitcnt lgkmcnt(0)
	v_add_f32_e32 v125, v125, v128
	s_nop 1
	v_mov_b32_dpp v128, v125 row_half_mirror row_mask:0xf bank_mask:0xf
	s_waitcnt lgkmcnt(0)
	v_add_f32_e32 v126, v126, v127
	s_nop 1
	v_mov_b32_dpp v127, v126 row_half_mirror row_mask:0xf bank_mask:0xf
	s_waitcnt lgkmcnt(0)
	v_add_f32_e32 v125, v125, v128
	s_nop 1
	v_mov_b32_dpp v130, v125 row_mirror row_mask:0xf bank_mask:0xf
	s_waitcnt lgkmcnt(0)
	v_add_f32_e32 v131, v126, v127
	s_waitcnt vmcnt(1)
	v_mov_b32_e32 v126, v155
	v_mov_b32_e32 v155, v157
	v_mov_b32_e32 v127, v156
	v_pk_mul_f32 v[128:129], v[154:155], v[112:113]
	s_nop 1
	v_mov_b32_dpp v132, v131 row_mirror row_mask:0xf bank_mask:0xf
	v_pk_fma_f32 v[126:127], v[126:127], v[108:109], v[128:129]
	s_waitcnt lgkmcnt(0)
	v_add_f32_e32 v130, v125, v130
	v_add_f32_e32 v133, v126, v127
	v_mov_b32_e32 v126, v143
	v_mov_b32_e32 v143, v145
	v_mov_b32_e32 v127, v144
	v_pk_mul_f32 v[128:129], v[142:143], v[112:113]
	s_nop 1
	v_mov_b32_dpp v154, v133 quad_perm:[1,0,3,2] row_mask:0xf bank_mask:0xf
	v_pk_fma_f32 v[126:127], v[126:127], v[108:109], v[128:129]
	v_mov_b32_e32 v129, v136
	v_add_f32_e32 v127, v126, v127
	s_nop 1
	v_mov_b32_dpp v128, v127 quad_perm:[1,0,3,2] row_mask:0xf bank_mask:0xf
	s_waitcnt lgkmcnt(0)
	v_add_f32_e32 v126, v131, v132
	s_waitcnt lgkmcnt(0)
	v_add_f32_e32 v125, v133, v154
	s_nop 1
	v_mov_b32_dpp v131, v125 quad_perm:[2,3,0,1] row_mask:0xf bank_mask:0xf
	s_waitcnt lgkmcnt(0)
	v_add_f32_e32 v127, v127, v128
	v_mov_b32_e32 v128, v135
	v_mov_b32_e32 v135, v137
	v_pk_mul_f32 v[132:133], v[134:135], v[112:113]
	s_nop 1
	v_mov_b32_dpp v142, v127 quad_perm:[2,3,0,1] row_mask:0xf bank_mask:0xf
	v_pk_fma_f32 v[128:129], v[128:129], v[108:109], v[132:133]
	s_waitcnt lgkmcnt(0)
	v_add_f32_e32 v125, v125, v131
	v_add_f32_e32 v128, v128, v129
	s_nop 1
	v_mov_b32_dpp v129, v128 quad_perm:[1,0,3,2] row_mask:0xf bank_mask:0xf
	s_waitcnt lgkmcnt(0)
	v_add_f32_e32 v127, v127, v142
	s_nop 1
	v_mov_b32_dpp v132, v127 row_half_mirror row_mask:0xf bank_mask:0xf
	s_nop 1
	v_mov_b32_dpp v131, v125 row_half_mirror row_mask:0xf bank_mask:0xf
	s_waitcnt lgkmcnt(0)
	v_add_f32_e32 v128, v128, v129
	s_nop 1
	v_mov_b32_dpp v129, v128 quad_perm:[2,3,0,1] row_mask:0xf bank_mask:0xf
	s_waitcnt lgkmcnt(0)
	v_add_f32_e32 v127, v127, v132
	s_waitcnt lgkmcnt(0)
	v_add_f32_e32 v125, v125, v131
	s_nop 1
	v_mov_b32_dpp v131, v125 row_mirror row_mask:0xf bank_mask:0xf
	s_nop 1
	v_mov_b32_dpp v134, v127 row_mirror row_mask:0xf bank_mask:0xf
	s_waitcnt lgkmcnt(0)
	v_add_f32_e32 v135, v128, v129
	v_mov_b32_e32 v128, v139
	v_mov_b32_e32 v139, v141
	v_mov_b32_e32 v129, v140
	v_pk_mul_f32 v[132:133], v[138:139], v[112:113]
	s_nop 1
	v_mov_b32_dpp v136, v135 row_half_mirror row_mask:0xf bank_mask:0xf
	v_pk_fma_f32 v[128:129], v[128:129], v[108:109], v[132:133]
	v_mov_b32_e32 v133, v152
	v_add_f32_e32 v129, v128, v129
	s_nop 1
	v_mov_b32_dpp v132, v129 quad_perm:[1,0,3,2] row_mask:0xf bank_mask:0xf
	s_waitcnt lgkmcnt(0)
	v_add_f32_e32 v128, v125, v131
	s_waitcnt lgkmcnt(0)
	v_add_f32_e32 v125, v127, v134
	s_waitcnt lgkmcnt(0)
	v_add_f32_e32 v127, v135, v136
	s_nop 1
	v_mov_b32_dpp v131, v127 row_mirror row_mask:0xf bank_mask:0xf
	s_waitcnt lgkmcnt(0)
	v_add_f32_e32 v129, v129, v132
	v_mov_b32_e32 v132, v151
	v_mov_b32_e32 v151, v153
	v_pk_mul_f32 v[134:135], v[150:151], v[112:113]
	s_nop 1
	v_mov_b32_dpp v136, v129 quad_perm:[2,3,0,1] row_mask:0xf bank_mask:0xf
	v_pk_fma_f32 v[132:133], v[132:133], v[108:109], v[134:135]
	s_waitcnt lgkmcnt(0)
	v_add_f32_e32 v129, v129, v136
	v_add_f32_e32 v137, v132, v133
	v_mov_b32_e32 v132, v147
	v_mov_b32_e32 v147, v149
	v_mov_b32_e32 v133, v148
	v_pk_mul_f32 v[134:135], v[146:147], v[112:113]
	s_nop 1
	v_mov_b32_dpp v138, v137 quad_perm:[1,0,3,2] row_mask:0xf bank_mask:0xf
	v_pk_fma_f32 v[132:133], v[132:133], v[108:109], v[134:135]
	s_nop 1
	v_mov_b32_dpp v134, v129 row_half_mirror row_mask:0xf bank_mask:0xf
	v_add_f32_e32 v132, v132, v133
	s_nop 1
	v_mov_b32_dpp v133, v132 quad_perm:[1,0,3,2] row_mask:0xf bank_mask:0xf
	s_waitcnt lgkmcnt(0)
	v_add_f32_e32 v135, v137, v138
	s_nop 1
	v_mov_b32_dpp v136, v135 quad_perm:[2,3,0,1] row_mask:0xf bank_mask:0xf
	s_waitcnt lgkmcnt(0)
	v_add_f32_e32 v134, v129, v134
	v_add_f32_e32 v129, v127, v131
	s_waitcnt lgkmcnt(0)
	v_add_f32_e32 v132, v132, v133
	s_nop 1
	v_mov_b32_dpp v133, v132 quad_perm:[2,3,0,1] row_mask:0xf bank_mask:0xf
	s_waitcnt lgkmcnt(0)
	v_add_f32_e32 v135, v135, v136
	s_nop 1
	v_mov_b32_dpp v136, v135 row_half_mirror row_mask:0xf bank_mask:0xf
	s_nop 1
	v_mov_b32_dpp v137, v134 row_mirror row_mask:0xf bank_mask:0xf
	s_waitcnt lgkmcnt(0)
	v_add_f32_e32 v132, v132, v133
	s_nop 1
	v_mov_b32_dpp v133, v132 row_half_mirror row_mask:0xf bank_mask:0xf
	s_waitcnt lgkmcnt(0)
	v_add_f32_e32 v131, v135, v136
	s_waitcnt lgkmcnt(0)
	v_add_f32_e32 v127, v134, v137
	s_nop 1
	v_mov_b32_dpp v134, v131 row_mirror row_mask:0xf bank_mask:0xf
	s_waitcnt lgkmcnt(0)
	v_add_f32_e32 v135, v132, v133
	v_mov_b32_e32 v132, v97
	v_mov_b32_e32 v97, v99
	v_mov_b32_e32 v133, v98
	v_pk_mul_f32 v[96:97], v[96:97], v[112:113]
	s_nop 1
	v_mov_b32_dpp v136, v135 row_mirror row_mask:0xf bank_mask:0xf
	v_pk_fma_f32 v[96:97], v[132:133], v[108:109], v[96:97]
	s_nop 0
	v_add_f32_e32 v98, v96, v97
	v_mov_b32_e32 v96, v93
	v_mov_b32_e32 v93, v95
	v_mov_b32_e32 v97, v94
	v_pk_mul_f32 v[92:93], v[92:93], v[112:113]
	s_nop 1
	v_mov_b32_dpp v99, v98 quad_perm:[1,0,3,2] row_mask:0xf bank_mask:0xf
	v_pk_fma_f32 v[92:93], v[96:97], v[108:109], v[92:93]
	s_waitcnt lgkmcnt(0)
	v_add_f32_e32 v96, v98, v99
	v_add_f32_e32 v94, v92, v93
	s_nop 1
	v_mov_b32_dpp v95, v94 quad_perm:[1,0,3,2] row_mask:0xf bank_mask:0xf
	s_nop 1
	v_mov_b32_dpp v97, v96 quad_perm:[2,3,0,1] row_mask:0xf bank_mask:0xf
	v_add_f32_e32 v93, v131, v134
	v_add_f32_e32 v92, v135, v136
	s_waitcnt lgkmcnt(0)
	v_add_f32_e32 v98, v94, v95
	v_mov_b32_e32 v94, v89
	v_mov_b32_e32 v89, v91
	v_mov_b32_e32 v95, v90
	v_pk_mul_f32 v[88:89], v[88:89], v[112:113]
	s_waitcnt lgkmcnt(0)
	v_add_f32_e32 v90, v96, v97
	v_pk_fma_f32 v[88:89], v[94:95], v[108:109], v[88:89]
	s_nop 1
	v_mov_b32_dpp v91, v90 row_half_mirror row_mask:0xf bank_mask:0xf
	v_add_f32_e32 v88, v88, v89
	s_nop 1
	v_mov_b32_dpp v89, v88 quad_perm:[1,0,3,2] row_mask:0xf bank_mask:0xf
	s_nop 1
	v_mov_b32_dpp v99, v98 quad_perm:[2,3,0,1] row_mask:0xf bank_mask:0xf
	s_waitcnt lgkmcnt(0)
	v_add_f32_e32 v90, v90, v91
	s_nop 1
	v_mov_b32_dpp v91, v90 row_mirror row_mask:0xf bank_mask:0xf
	s_waitcnt lgkmcnt(0)
	v_add_f32_e32 v88, v88, v89
	s_nop 1
	v_mov_b32_dpp v89, v88 quad_perm:[2,3,0,1] row_mask:0xf bank_mask:0xf
	s_waitcnt lgkmcnt(0)
	v_add_f32_e32 v94, v98, v99
	s_nop 1
	v_mov_b32_dpp v95, v94 row_half_mirror row_mask:0xf bank_mask:0xf
	s_waitcnt lgkmcnt(0)
	v_add_f32_e32 v96, v88, v89
	v_mov_b32_e32 v88, v85
	v_mov_b32_e32 v85, v87
	v_mov_b32_e32 v89, v86
	v_pk_mul_f32 v[84:85], v[84:85], v[112:113]
	s_nop 1
	v_mov_b32_dpp v97, v96 row_half_mirror row_mask:0xf bank_mask:0xf
	v_pk_fma_f32 v[84:85], v[88:89], v[108:109], v[84:85]
	s_waitcnt lgkmcnt(0)
	v_add_f32_e32 v94, v94, v95
	v_add_f32_e32 v86, v84, v85
	s_nop 1
	v_mov_b32_dpp v87, v86 quad_perm:[1,0,3,2] row_mask:0xf bank_mask:0xf
	v_add_f32_e32 v85, v90, v91
	s_waitcnt lgkmcnt(0)
	v_add_f32_e32 v88, v96, v97
	s_nop 1
	v_mov_b32_dpp v95, v94 row_mirror row_mask:0xf bank_mask:0xf
	s_nop 1
	v_mov_b32_dpp v89, v88 row_mirror row_mask:0xf bank_mask:0xf
	s_waitcnt lgkmcnt(0)
	v_add_f32_e32 v90, v86, v87
	v_mov_b32_e32 v86, v81
	v_mov_b32_e32 v81, v83
	s_nop 1
	v_mov_b32_dpp v91, v90 quad_perm:[2,3,0,1] row_mask:0xf bank_mask:0xf
	v_mov_b32_e32 v87, v82
	v_pk_mul_f32 v[80:81], v[80:81], v[112:113]
	s_waitcnt lgkmcnt(0)
	v_add_f32_e32 v84, v94, v95
	v_pk_fma_f32 v[80:81], v[86:87], v[108:109], v[80:81]
	s_nop 0
	v_add_f32_e32 v82, v80, v81
	v_mov_b32_e32 v80, v77
	v_mov_b32_e32 v77, v79
	v_mov_b32_e32 v81, v78
	v_pk_mul_f32 v[76:77], v[76:77], v[112:113]
	s_waitcnt lgkmcnt(0)
	v_add_f32_e32 v78, v90, v91
	v_pk_fma_f32 v[76:77], v[80:81], v[108:109], v[76:77]
	s_nop 1
	v_mov_b32_dpp v79, v78 row_half_mirror row_mask:0xf bank_mask:0xf
	v_add_f32_e32 v76, v76, v77
	s_nop 1
	v_mov_b32_dpp v77, v76 quad_perm:[1,0,3,2] row_mask:0xf bank_mask:0xf
	s_nop 1
	v_mov_b32_dpp v83, v82 quad_perm:[1,0,3,2] row_mask:0xf bank_mask:0xf
	s_waitcnt lgkmcnt(0)
	v_add_f32_e32 v78, v78, v79
	s_nop 1
	v_mov_b32_dpp v79, v78 row_mirror row_mask:0xf bank_mask:0xf
	s_waitcnt lgkmcnt(0)
	v_add_f32_e32 v76, v76, v77
	s_nop 1
	v_mov_b32_dpp v77, v76 quad_perm:[2,3,0,1] row_mask:0xf bank_mask:0xf
	s_waitcnt lgkmcnt(0)
	v_add_f32_e32 v80, v82, v83
	s_nop 1
	v_mov_b32_dpp v81, v80 quad_perm:[2,3,0,1] row_mask:0xf bank_mask:0xf
	s_waitcnt lgkmcnt(0)
	v_add_f32_e32 v82, v76, v77
	v_add_f32_e32 v76, v78, v79
	v_mov_b32_e32 v78, v73
	v_mov_b32_e32 v73, v75
	v_mov_b32_e32 v79, v74
	v_pk_mul_f32 v[72:73], v[72:73], v[112:113]
	s_nop 1
	v_mov_b32_dpp v83, v82 row_half_mirror row_mask:0xf bank_mask:0xf
	v_pk_fma_f32 v[72:73], v[78:79], v[108:109], v[72:73]
	s_waitcnt lgkmcnt(0)
	v_add_f32_e32 v80, v80, v81
	v_add_f32_e32 v74, v72, v73
	v_mov_b32_e32 v72, v69
	v_mov_b32_e32 v69, v71
	v_mov_b32_e32 v73, v70
	v_pk_mul_f32 v[68:69], v[68:69], v[112:113]
	s_nop 1
	v_mov_b32_dpp v75, v74 quad_perm:[1,0,3,2] row_mask:0xf bank_mask:0xf
	v_pk_fma_f32 v[68:69], v[72:73], v[108:109], v[68:69]
	s_waitcnt lgkmcnt(0)
	v_add_f32_e32 v82, v82, v83
	v_add_f32_e32 v70, v68, v69
	s_nop 1
	v_mov_b32_dpp v71, v70 quad_perm:[1,0,3,2] row_mask:0xf bank_mask:0xf
	s_waitcnt lgkmcnt(0)
	v_add_f32_e32 v72, v74, v75
	s_nop 1
	v_mov_b32_dpp v73, v72 quad_perm:[2,3,0,1] row_mask:0xf bank_mask:0xf
	s_nop 1
	v_mov_b32_dpp v83, v82 row_mirror row_mask:0xf bank_mask:0xf
	s_nop 1
	v_mov_b32_dpp v81, v80 row_half_mirror row_mask:0xf bank_mask:0xf
	s_waitcnt lgkmcnt(0)
	v_add_f32_e32 v74, v70, v71
	v_mov_b32_e32 v70, v65
	v_mov_b32_e32 v65, v67
	v_mov_b32_e32 v71, v66
	v_pk_mul_f32 v[64:65], v[64:65], v[112:113]
	s_waitcnt lgkmcnt(0)
	v_add_f32_e32 v66, v72, v73
	v_pk_fma_f32 v[64:65], v[70:71], v[108:109], v[64:65]
	s_nop 1
	v_mov_b32_dpp v67, v66 row_half_mirror row_mask:0xf bank_mask:0xf
	v_add_f32_e32 v64, v64, v65
	s_nop 1
	v_mov_b32_dpp v65, v64 quad_perm:[1,0,3,2] row_mask:0xf bank_mask:0xf
	s_nop 1
	v_mov_b32_dpp v75, v74 quad_perm:[2,3,0,1] row_mask:0xf bank_mask:0xf
	s_waitcnt lgkmcnt(0)
	v_add_f32_e32 v68, v82, v83
	s_waitcnt lgkmcnt(0)
	v_add_f32_e32 v66, v66, v67
	s_nop 1
	v_mov_b32_dpp v67, v66 row_mirror row_mask:0xf bank_mask:0xf
	s_waitcnt lgkmcnt(0)
	v_add_f32_e32 v64, v64, v65
	s_nop 1
	v_mov_b32_dpp v65, v64 quad_perm:[2,3,0,1] row_mask:0xf bank_mask:0xf
	s_waitcnt lgkmcnt(0)
	v_add_f32_e32 v70, v74, v75
	s_nop 1
	v_mov_b32_dpp v71, v70 row_half_mirror row_mask:0xf bank_mask:0xf
	s_waitcnt lgkmcnt(0)
	v_add_f32_e32 v66, v66, v67
	v_add_f32_e32 v80, v80, v81
	s_waitcnt lgkmcnt(0)
	v_add_f32_e32 v72, v64, v65
	v_mov_b32_e32 v64, v61
	v_mov_b32_e32 v61, v63
	v_mov_b32_e32 v65, v62
	v_pk_mul_f32 v[60:61], v[60:61], v[112:113]
	s_nop 1
	v_mov_b32_dpp v81, v80 row_mirror row_mask:0xf bank_mask:0xf
	v_pk_fma_f32 v[60:61], v[64:65], v[108:109], v[60:61]
	s_nop 1
	v_mov_b32_dpp v73, v72 row_half_mirror row_mask:0xf bank_mask:0xf
	v_add_f32_e32 v60, v60, v61
	s_nop 1
	v_mov_b32_dpp v61, v60 quad_perm:[1,0,3,2] row_mask:0xf bank_mask:0xf
	s_waitcnt lgkmcnt(0)
	v_add_f32_e32 v70, v70, v71
	s_nop 1
	v_mov_b32_dpp v71, v70 row_mirror row_mask:0xf bank_mask:0xf
	v_add_f32_e32 v77, v88, v89
	s_waitcnt lgkmcnt(0)
	v_add_f32_e32 v69, v80, v81
	s_waitcnt lgkmcnt(0)
	v_add_f32_e32 v65, v60, v61
	v_mov_b32_e32 v60, v57
	v_mov_b32_e32 v57, v59
	v_mov_b32_e32 v61, v58
	v_pk_mul_f32 v[56:57], v[56:57], v[112:113]
	s_nop 1
	v_mov_b32_dpp v67, v65 quad_perm:[2,3,0,1] row_mask:0xf bank_mask:0xf
	v_pk_fma_f32 v[56:57], v[60:61], v[108:109], v[56:57]
	v_add_f32_e32 v62, v72, v73
	v_add_f32_e32 v58, v56, v57
	v_mov_b32_e32 v56, v53
	v_mov_b32_e32 v53, v55
	v_mov_b32_e32 v57, v54
	v_pk_mul_f32 v[52:53], v[52:53], v[112:113]
	s_nop 1
	v_mov_b32_dpp v59, v58 quad_perm:[1,0,3,2] row_mask:0xf bank_mask:0xf
	v_pk_fma_f32 v[52:53], v[56:57], v[108:109], v[52:53]
	s_waitcnt lgkmcnt(0)
	v_add_f32_e32 v54, v65, v67
	v_add_f32_e32 v52, v52, v53
	s_nop 1
	v_mov_b32_dpp v53, v52 quad_perm:[1,0,3,2] row_mask:0xf bank_mask:0xf
	s_waitcnt lgkmcnt(0)
	v_add_f32_e32 v56, v58, v59
	s_nop 1
	v_mov_b32_dpp v55, v54 row_half_mirror row_mask:0xf bank_mask:0xf
	s_nop 1
	v_mov_b32_dpp v57, v56 quad_perm:[2,3,0,1] row_mask:0xf bank_mask:0xf
	s_nop 1
	v_mov_b32_dpp v63, v62 row_mirror row_mask:0xf bank_mask:0xf
	s_waitcnt lgkmcnt(0)
	v_add_f32_e32 v52, v52, v53
	s_nop 1
	v_mov_b32_dpp v53, v52 quad_perm:[2,3,0,1] row_mask:0xf bank_mask:0xf
	s_waitcnt lgkmcnt(0)
	v_add_f32_e32 v54, v54, v55
	s_waitcnt lgkmcnt(0)
	v_add_f32_e32 v56, v56, v57
	s_nop 1
	v_mov_b32_dpp v55, v54 row_mirror row_mask:0xf bank_mask:0xf
	s_nop 1
	v_mov_b32_dpp v57, v56 row_half_mirror row_mask:0xf bank_mask:0xf
	s_waitcnt lgkmcnt(0)
	v_add_f32_e32 v52, v52, v53
	s_nop 1
	v_mov_b32_dpp v53, v52 row_half_mirror row_mask:0xf bank_mask:0xf
	v_add_f32_e32 v64, v70, v71
	s_waitcnt lgkmcnt(0)
	v_add_f32_e32 v58, v54, v55
	s_waitcnt lgkmcnt(0)
	v_add_f32_e32 v54, v56, v57
	s_nop 1
	v_mov_b32_dpp v55, v54 row_mirror row_mask:0xf bank_mask:0xf
	s_waitcnt lgkmcnt(0)
	v_add_f32_e32 v56, v52, v53
	v_mov_b32_e32 v52, v49
	v_mov_b32_e32 v49, v51
	v_mov_b32_e32 v53, v50
	v_pk_mul_f32 v[48:49], v[48:49], v[112:113]
	s_waitcnt lgkmcnt(0)
	v_add_f32_e32 v61, v54, v55
	v_pk_fma_f32 v[48:49], v[52:53], v[108:109], v[48:49]
	s_nop 1
	v_mov_b32_dpp v57, v56 row_mirror row_mask:0xf bank_mask:0xf
	v_add_f32_e32 v50, v48, v49
	v_mov_b32_e32 v48, v45
	v_mov_b32_e32 v45, v47
	v_mov_b32_e32 v49, v46
	v_pk_mul_f32 v[44:45], v[44:45], v[112:113]
	s_nop 1
	v_mov_b32_dpp v51, v50 quad_perm:[1,0,3,2] row_mask:0xf bank_mask:0xf
	v_pk_fma_f32 v[44:45], v[48:49], v[108:109], v[44:45]
	s_waitcnt lgkmcnt(0)
	v_add_f32_e32 v57, v56, v57
	v_add_f32_e32 v44, v44, v45
	s_nop 1
	v_mov_b32_dpp v45, v44 quad_perm:[1,0,3,2] row_mask:0xf bank_mask:0xf
	s_waitcnt lgkmcnt(0)
	v_add_f32_e32 v46, v50, v51
	s_nop 1
	v_mov_b32_dpp v47, v46 quad_perm:[2,3,0,1] row_mask:0xf bank_mask:0xf
	v_add_f32_e32 v62, v62, v63
	s_waitcnt lgkmcnt(0)
	v_add_f32_e32 v48, v44, v45
	v_mov_b32_e32 v44, v41
	v_mov_b32_e32 v41, v43
	v_mov_b32_e32 v45, v42
	v_pk_mul_f32 v[40:41], v[40:41], v[112:113]
	s_waitcnt lgkmcnt(0)
	v_add_f32_e32 v42, v46, v47
	v_pk_fma_f32 v[40:41], v[44:45], v[108:109], v[40:41]
	s_nop 1
	v_mov_b32_dpp v49, v48 quad_perm:[2,3,0,1] row_mask:0xf bank_mask:0xf
	v_add_f32_e32 v40, v40, v41
	s_nop 1
	v_mov_b32_dpp v41, v40 quad_perm:[1,0,3,2] row_mask:0xf bank_mask:0xf
	s_nop 1
	v_mov_b32_dpp v43, v42 row_half_mirror row_mask:0xf bank_mask:0xf
	s_waitcnt lgkmcnt(0)
	v_add_f32_e32 v44, v48, v49
	s_nop 1
	v_mov_b32_dpp v45, v44 row_half_mirror row_mask:0xf bank_mask:0xf
	s_waitcnt lgkmcnt(0)
	v_add_f32_e32 v40, v40, v41
	s_nop 1
	v_mov_b32_dpp v41, v40 quad_perm:[2,3,0,1] row_mask:0xf bank_mask:0xf
	v_lshl_add_u64 v[48:49], v[102:103], 0, v[110:111]
	s_waitcnt lgkmcnt(0)
	v_add_f32_e32 v42, v42, v43
	s_waitcnt lgkmcnt(0)
	v_add_f32_e32 v44, v44, v45
	s_nop 1
	v_mov_b32_dpp v43, v42 row_mirror row_mask:0xf bank_mask:0xf
	s_waitcnt lgkmcnt(0)
	v_add_f32_e32 v46, v40, v41
	v_mov_b32_e32 v40, v37
	v_mov_b32_e32 v37, v39
	v_mov_b32_e32 v41, v38
	v_pk_mul_f32 v[36:37], v[36:37], v[112:113]
	s_nop 1
	v_mov_b32_dpp v45, v44 row_mirror row_mask:0xf bank_mask:0xf
	v_pk_fma_f32 v[36:37], v[40:41], v[108:109], v[36:37]
	s_nop 1
	v_mov_b32_dpp v47, v46 row_half_mirror row_mask:0xf bank_mask:0xf
	v_add_f32_e32 v36, v36, v37
	s_nop 1
	v_mov_b32_dpp v37, v36 quad_perm:[1,0,3,2] row_mask:0xf bank_mask:0xf
	s_waitcnt lgkmcnt(0)
	v_add_f32_e32 v60, v42, v43
	s_waitcnt lgkmcnt(0)
	v_add_f32_e32 v56, v44, v45
	s_waitcnt lgkmcnt(0)
	v_add_f32_e32 v38, v46, v47
	global_load_dwordx4 v[78:81], v[48:49], off
	global_load_dwordx4 v[86:89], v[48:49], off offset:2048
	s_waitcnt lgkmcnt(0)
	v_add_f32_e32 v40, v36, v37
	v_mov_b32_e32 v36, v33
	v_mov_b32_e32 v33, v35
	v_mov_b32_e32 v37, v34
	v_pk_mul_f32 v[32:33], v[32:33], v[112:113]
	s_nop 1
	v_mov_b32_dpp v41, v40 quad_perm:[2,3,0,1] row_mask:0xf bank_mask:0xf
	v_pk_fma_f32 v[32:33], v[36:37], v[108:109], v[32:33]
	s_nop 1
	v_mov_b32_dpp v39, v38 row_mirror row_mask:0xf bank_mask:0xf
	v_add_f32_e32 v34, v32, v33
	v_mov_b32_e32 v32, v29
	v_mov_b32_e32 v29, v31
	v_mov_b32_e32 v33, v30
	v_pk_mul_f32 v[28:29], v[28:29], v[112:113]
	s_nop 1
	v_mov_b32_dpp v35, v34 quad_perm:[1,0,3,2] row_mask:0xf bank_mask:0xf
	v_pk_fma_f32 v[28:29], v[32:33], v[108:109], v[28:29]
	s_waitcnt lgkmcnt(0)
	v_add_f32_e32 v30, v40, v41
	v_add_f32_e32 v28, v28, v29
	s_nop 1
	v_mov_b32_dpp v29, v28 quad_perm:[1,0,3,2] row_mask:0xf bank_mask:0xf
	s_waitcnt lgkmcnt(0)
	v_add_f32_e32 v32, v34, v35
	s_nop 1
	v_mov_b32_dpp v33, v32 quad_perm:[2,3,0,1] row_mask:0xf bank_mask:0xf
	s_nop 1
	v_mov_b32_dpp v31, v30 row_half_mirror row_mask:0xf bank_mask:0xf
	v_add_f32_e32 v63, v38, v39
	s_waitcnt lgkmcnt(0)
	v_add_f32_e32 v28, v28, v29
	s_nop 1
	v_mov_b32_dpp v29, v28 quad_perm:[2,3,0,1] row_mask:0xf bank_mask:0xf
	s_waitcnt lgkmcnt(0)
	v_add_f32_e32 v32, v32, v33
	s_nop 1
	v_mov_b32_dpp v33, v32 row_half_mirror row_mask:0xf bank_mask:0xf
	s_waitcnt lgkmcnt(0)
	v_add_f32_e32 v30, v30, v31
	s_nop 1
	v_mov_b32_dpp v31, v30 row_mirror row_mask:0xf bank_mask:0xf
	s_waitcnt lgkmcnt(0)
	v_add_f32_e32 v34, v28, v29
	v_mov_b32_e32 v28, v25
	v_mov_b32_e32 v25, v27
	v_mov_b32_e32 v29, v26
	v_pk_mul_f32 v[24:25], v[24:25], v[112:113]
	s_waitcnt lgkmcnt(0)
	v_add_f32_e32 v26, v32, v33
	v_pk_fma_f32 v[24:25], v[28:29], v[108:109], v[24:25]
	s_nop 1
	v_mov_b32_dpp v27, v26 row_mirror row_mask:0xf bank_mask:0xf
	v_add_f32_e32 v24, v24, v25
	s_nop 1
	v_mov_b32_dpp v25, v24 quad_perm:[1,0,3,2] row_mask:0xf bank_mask:0xf
	s_nop 1
	v_mov_b32_dpp v35, v34 row_half_mirror row_mask:0xf bank_mask:0xf
	s_waitcnt lgkmcnt(0)
	v_add_f32_e32 v59, v30, v31
	s_waitcnt lgkmcnt(0)
	v_add_f32_e32 v54, v26, v27
	s_waitcnt lgkmcnt(0)
	v_add_f32_e32 v24, v24, v25
	s_nop 1
	v_mov_b32_dpp v25, v24 quad_perm:[2,3,0,1] row_mask:0xf bank_mask:0xf
	s_waitcnt lgkmcnt(0)
	v_add_f32_e32 v28, v34, v35
	s_nop 1
	v_mov_b32_dpp v29, v28 row_mirror row_mask:0xf bank_mask:0xf
	s_waitcnt lgkmcnt(0)
	v_add_f32_e32 v26, v24, v25
	v_mov_b32_e32 v24, v21
	v_mov_b32_e32 v21, v23
	v_mov_b32_e32 v25, v22
	v_pk_mul_f32 v[20:21], v[20:21], v[112:113]
	s_nop 1
	v_mov_b32_dpp v27, v26 row_half_mirror row_mask:0xf bank_mask:0xf
	v_pk_fma_f32 v[20:21], v[24:25], v[108:109], v[20:21]
	s_waitcnt lgkmcnt(0)
	v_add_f32_e32 v52, v28, v29
	v_add_f32_e32 v22, v20, v21
	v_mov_b32_e32 v20, v17
	v_mov_b32_e32 v17, v19
	v_mov_b32_e32 v21, v18
	v_pk_mul_f32 v[16:17], v[16:17], v[112:113]
	s_nop 1
	v_mov_b32_dpp v23, v22 quad_perm:[1,0,3,2] row_mask:0xf bank_mask:0xf
	v_pk_fma_f32 v[16:17], v[20:21], v[108:109], v[16:17]
	s_waitcnt lgkmcnt(0)
	v_add_f32_e32 v53, v26, v27
	v_add_f32_e32 v16, v16, v17
	s_nop 1
	v_mov_b32_dpp v17, v16 quad_perm:[1,0,3,2] row_mask:0xf bank_mask:0xf
	s_waitcnt lgkmcnt(0)
	v_add_f32_e32 v18, v22, v23
	s_nop 1
	v_mov_b32_dpp v19, v18 quad_perm:[2,3,0,1] row_mask:0xf bank_mask:0xf
	s_nop 1
	v_mov_b32_dpp v55, v53 row_mirror row_mask:0xf bank_mask:0xf
	s_waitcnt lgkmcnt(0)
	v_add_f32_e32 v20, v16, v17
	v_mov_b32_e32 v16, v13
	v_mov_b32_e32 v13, v15
	v_mov_b32_e32 v17, v14
	v_pk_mul_f32 v[12:13], v[12:13], v[112:113]
	s_nop 1
	v_mov_b32_dpp v21, v20 quad_perm:[2,3,0,1] row_mask:0xf bank_mask:0xf
	v_pk_fma_f32 v[12:13], v[16:17], v[108:109], v[12:13]
	s_waitcnt lgkmcnt(0)
	v_add_f32_e32 v14, v18, v19
	v_add_f32_e32 v12, v12, v13
	s_nop 1
	v_mov_b32_dpp v13, v12 quad_perm:[1,0,3,2] row_mask:0xf bank_mask:0xf
	s_nop 1
	v_mov_b32_dpp v15, v14 row_half_mirror row_mask:0xf bank_mask:0xf
	s_waitcnt lgkmcnt(0)
	v_add_f32_e32 v16, v20, v21
	s_nop 1
	v_mov_b32_dpp v17, v16 row_half_mirror row_mask:0xf bank_mask:0xf
	v_add_f32_e32 v73, v53, v55
	s_waitcnt lgkmcnt(0)
	v_add_f32_e32 v12, v12, v13
	s_nop 1
	v_mov_b32_dpp v13, v12 quad_perm:[2,3,0,1] row_mask:0xf bank_mask:0xf
	s_waitcnt lgkmcnt(0)
	v_add_f32_e32 v65, v14, v15
	s_waitcnt lgkmcnt(0)
	v_add_f32_e32 v74, v16, v17
	s_nop 1
	v_mov_b32_dpp v75, v74 row_mirror row_mask:0xf bank_mask:0xf
	s_nop 1
	v_mov_b32_dpp v67, v65 row_mirror row_mask:0xf bank_mask:0xf
	s_waitcnt lgkmcnt(0)
	v_add_f32_e32 v82, v12, v13
	v_add_co_u32_e32 v12, vcc, s17, v48
	s_nop 1
	v_mov_b32_dpp v83, v82 row_half_mirror row_mask:0xf bank_mask:0xf
	s_nop 0
	v_addc_co_u32_e32 v13, vcc, 0, v49, vcc
	v_add_co_u32_e32 v14, vcc, s91, v48
	s_waitcnt lgkmcnt(0)
	v_add_f32_e32 v53, v82, v83
	v_addc_co_u32_e32 v15, vcc, 0, v49, vcc
	v_add_co_u32_e32 v16, vcc, s50, v48
	global_load_dwordx4 v[94:97], v[14:15], off offset:-4096
	global_load_dwordx4 v[132:135], v[14:15], off
	v_addc_co_u32_e32 v17, vcc, 0, v49, vcc
	v_add_co_u32_e32 v18, vcc, s90, v48
	s_nop 1
	v_mov_b32_dpp v55, v53 row_mirror row_mask:0xf bank_mask:0xf
	s_nop 0
	v_addc_co_u32_e32 v19, vcc, 0, v49, vcc
	global_load_dwordx4 v[136:139], v[14:15], off offset:2048
	global_load_dwordx4 v[140:143], v[18:19], off offset:-4096
	global_load_dwordx4 v[144:147], v[12:13], off offset:2048
	global_load_dwordx4 v[44:47], v[16:17], off offset:2048
	global_load_dwordx4 v[40:43], v[18:19], off
	global_load_dwordx4 v[32:35], v[18:19], off offset:2048
	v_add_co_u32_e32 v12, vcc, s96, v48
	v_add_f32_e32 v72, v65, v67
	s_nop 0
	v_addc_co_u32_e32 v13, vcc, 0, v49, vcc
	v_add_co_u32_e32 v14, vcc, s1, v48
	s_nop 1
	v_addc_co_u32_e32 v15, vcc, 0, v49, vcc
	v_add_co_u32_e32 v70, vcc, s51, v48
	global_load_dwordx4 v[36:39], v[14:15], off offset:-4096
	global_load_dwordx4 v[24:27], v[14:15], off
	v_addc_co_u32_e32 v71, vcc, 0, v49, vcc
	v_add_co_u32_e32 v50, vcc, s92, v48
	s_nop 1
	v_addc_co_u32_e32 v51, vcc, 0, v49, vcc
	global_load_dwordx4 v[20:23], v[14:15], off offset:2048
	global_load_dwordx4 v[16:19], v[50:51], off offset:-4096
	global_load_dwordx4 v[28:31], v[12:13], off offset:2048
	s_nop 0
	global_load_dwordx4 v[12:15], v[70:71], off offset:2048
	v_add_f32_e32 v70, v74, v75
	v_mov_b32_e32 v74, v9
	v_mov_b32_e32 v9, v11
	v_mov_b32_e32 v75, v10
	v_pk_mul_f32 v[8:9], v[8:9], v[112:113]
	s_waitcnt lgkmcnt(0)
	v_add_f32_e32 v71, v53, v55
	v_pk_fma_f32 v[8:9], v[74:75], v[108:109], v[8:9]
	s_nop 0
	v_add_f32_e32 v10, v8, v9
	s_waitcnt vmcnt(16)
	v_mov_b32_e32 v8, v5
	v_mov_b32_e32 v9, v6
	v_mov_b32_e32 v5, v7
	v_mul_f32_e32 v6, v108, v123
	v_mul_f32_e32 v7, v113, v124
	v_pk_mul_f32 v[4:5], v[4:5], v[112:113]
	v_fmac_f32_e32 v6, v112, v121
	v_fmac_f32_e32 v7, v109, v122
	v_pk_fma_f32 v[4:5], v[8:9], v[108:109], v[4:5]
	v_add_f32_e32 v6, v6, v7
	v_add_f32_e32 v4, v4, v5
	s_nop 1
	v_mov_b32_dpp v7, v6 quad_perm:[1,0,3,2] row_mask:0xf bank_mask:0xf
	s_nop 1
	v_mov_b32_dpp v5, v4 quad_perm:[1,0,3,2] row_mask:0xf bank_mask:0xf
	s_nop 1
	v_mov_b32_dpp v11, v10 quad_perm:[1,0,3,2] row_mask:0xf bank_mask:0xf
	s_waitcnt lgkmcnt(0)
	v_add_f32_e32 v6, v6, v7
	s_waitcnt lgkmcnt(0)
	v_add_f32_e32 v4, v4, v5
	s_nop 1
	v_mov_b32_dpp v7, v6 quad_perm:[2,3,0,1] row_mask:0xf bank_mask:0xf
	s_nop 1
	v_mov_b32_dpp v5, v4 quad_perm:[2,3,0,1] row_mask:0xf bank_mask:0xf
	s_waitcnt lgkmcnt(0)
	v_add_f32_e32 v8, v10, v11
	s_nop 1
	v_mov_b32_dpp v9, v8 quad_perm:[2,3,0,1] row_mask:0xf bank_mask:0xf
	s_waitcnt lgkmcnt(0)
	v_add_f32_e32 v6, v6, v7
	s_waitcnt lgkmcnt(0)
	v_add_f32_e32 v4, v4, v5
	s_nop 1
	v_mov_b32_dpp v7, v6 row_half_mirror row_mask:0xf bank_mask:0xf
	s_nop 1
	v_mov_b32_dpp v5, v4 row_half_mirror row_mask:0xf bank_mask:0xf
	s_waitcnt lgkmcnt(0)
	v_add_f32_e32 v8, v8, v9
	s_nop 1
	v_mov_b32_dpp v9, v8 row_half_mirror row_mask:0xf bank_mask:0xf
	s_waitcnt lgkmcnt(0)
	v_add_f32_e32 v6, v6, v7
	s_waitcnt lgkmcnt(0)
	v_add_f32_e32 v4, v4, v5
	s_nop 1
	v_mov_b32_dpp v7, v6 row_mirror row_mask:0xf bank_mask:0xf
	s_nop 1
	v_mov_b32_dpp v5, v4 row_mirror row_mask:0xf bank_mask:0xf
	s_waitcnt lgkmcnt(0)
	v_add_f32_e32 v8, v8, v9
	s_nop 1
	v_mov_b32_dpp v9, v8 row_mirror row_mask:0xf bank_mask:0xf
	s_waitcnt lgkmcnt(0)
	v_add_f32_e32 v53, v6, v7
	s_waitcnt lgkmcnt(0)
	v_add_f32_e32 v65, v4, v5
	v_cndmask_b32_e64 v4, v130, v237, s[38:39]
	v_max_f32_e32 v5, v53, v120
	v_max3_f32 v5, v5, v4, v126
	v_max3_f32 v5, v5, v128, v125
	v_max3_f32 v5, v5, v129, v127
	v_max3_f32 v5, v5, v93, v92
	v_max3_f32 v5, v5, v85, v84
	v_max3_f32 v5, v5, v77, v76
	v_max3_f32 v5, v5, v69, v68
	v_max3_f32 v5, v5, v66, v64
	v_max3_f32 v5, v5, v62, v58
	v_max3_f32 v5, v5, v61, v57
	v_max3_f32 v5, v5, v60, v56
	v_max3_f32 v5, v5, v63, v59
	v_max3_f32 v5, v5, v54, v52
	v_max3_f32 v5, v5, v73, v72
	s_waitcnt lgkmcnt(0)
	v_add_f32_e32 v67, v8, v9
	v_max3_f32 v5, v5, v70, v71
	v_max3_f32 v5, v5, v67, v65
	ds_bpermute_b32 v6, v118, v5
	s_waitcnt lgkmcnt(0)
	v_max_f32_e32 v6, v6, v6
	v_max_f32_e32 v5, v5, v6
	ds_bpermute_b32 v6, v119, v5
	s_waitcnt lgkmcnt(0)
	v_max_f32_e32 v6, v6, v6
	v_max_f32_e32 v55, v5, v6
	v_sub_f32_e32 v4, v4, v55
	v_exp_f32_e32 v4, v4
	v_sub_f32_e32 v8, v126, v55
	v_exp_f32_e32 v8, v8
	v_add_f32_e32 v9, 0, v4
	s_waitcnt vmcnt(15)
	v_pk_fma_f32 v[6:7], v[78:79], v[4:5], 0 op_sel_hi:[1,0,0]
	v_pk_fma_f32 v[4:5], v[80:81], v[4:5], 0 op_sel_hi:[1,0,0]
	v_add_f32_e32 v9, v8, v9
	s_waitcnt vmcnt(14)
	v_pk_fma_f32 v[4:5], v[88:89], v[8:9], v[4:5] op_sel_hi:[1,0,1]
	v_pk_fma_f32 v[6:7], v[86:87], v[8:9], v[6:7] op_sel_hi:[1,0,1]
	v_sub_f32_e32 v8, v128, v55
	v_exp_f32_e32 v8, v8
	s_nop 0
	v_add_f32_e32 v9, v8, v9
	s_waitcnt vmcnt(13)
	v_pk_fma_f32 v[6:7], v[94:95], v[8:9], v[6:7] op_sel_hi:[1,0,1]
	v_pk_fma_f32 v[4:5], v[96:97], v[8:9], v[4:5] op_sel_hi:[1,0,1]
	v_sub_f32_e32 v8, v125, v55
	v_exp_f32_e32 v8, v8
	s_nop 0
	v_add_f32_e32 v9, v8, v9
	s_waitcnt vmcnt(9)
	v_pk_fma_f32 v[4:5], v[146:147], v[8:9], v[4:5] op_sel_hi:[1,0,1]
	v_pk_fma_f32 v[6:7], v[144:145], v[8:9], v[6:7] op_sel_hi:[1,0,1]
	v_sub_f32_e32 v8, v129, v55
	v_exp_f32_e32 v8, v8
	s_nop 0
	v_add_f32_e32 v9, v8, v9
	v_pk_fma_f32 v[6:7], v[132:133], v[8:9], v[6:7] op_sel_hi:[1,0,1]
	v_pk_fma_f32 v[4:5], v[134:135], v[8:9], v[4:5] op_sel_hi:[1,0,1]
	v_sub_f32_e32 v8, v127, v55
	v_exp_f32_e32 v8, v8
	s_nop 0
	v_add_f32_e32 v9, v8, v9
	v_pk_fma_f32 v[4:5], v[138:139], v[8:9], v[4:5] op_sel_hi:[1,0,1]
	v_pk_fma_f32 v[6:7], v[136:137], v[8:9], v[6:7] op_sel_hi:[1,0,1]
	v_sub_f32_e32 v8, v93, v55
	v_exp_f32_e32 v8, v8
	s_nop 0
	v_add_f32_e32 v9, v8, v9
	v_pk_fma_f32 v[6:7], v[140:141], v[8:9], v[6:7] op_sel_hi:[1,0,1]
	v_pk_fma_f32 v[4:5], v[142:143], v[8:9], v[4:5] op_sel_hi:[1,0,1]
	v_sub_f32_e32 v8, v92, v55
	v_exp_f32_e32 v8, v8
	s_nop 0
	v_add_f32_e32 v9, v8, v9
	s_waitcnt vmcnt(8)
	v_pk_fma_f32 v[4:5], v[46:47], v[8:9], v[4:5] op_sel_hi:[1,0,1]
	v_pk_fma_f32 v[6:7], v[44:45], v[8:9], v[6:7] op_sel_hi:[1,0,1]
	v_sub_f32_e32 v8, v85, v55
	v_exp_f32_e32 v8, v8
	s_nop 0
	v_add_f32_e32 v9, v8, v9
	s_waitcnt vmcnt(7)
	v_pk_fma_f32 v[6:7], v[40:41], v[8:9], v[6:7] op_sel_hi:[1,0,1]
	v_pk_fma_f32 v[4:5], v[42:43], v[8:9], v[4:5] op_sel_hi:[1,0,1]
	v_sub_f32_e32 v8, v84, v55
	v_exp_f32_e32 v8, v8
	s_nop 0
	v_add_f32_e32 v9, v8, v9
	s_waitcnt vmcnt(6)
	v_pk_fma_f32 v[4:5], v[34:35], v[8:9], v[4:5] op_sel_hi:[1,0,1]
	v_pk_fma_f32 v[6:7], v[32:33], v[8:9], v[6:7] op_sel_hi:[1,0,1]
	v_sub_f32_e32 v8, v77, v55
	v_exp_f32_e32 v8, v8
	s_nop 0
	v_add_f32_e32 v9, v8, v9
	s_waitcnt vmcnt(5)
	v_pk_fma_f32 v[6:7], v[36:37], v[8:9], v[6:7] op_sel_hi:[1,0,1]
	v_pk_fma_f32 v[4:5], v[38:39], v[8:9], v[4:5] op_sel_hi:[1,0,1]
	v_sub_f32_e32 v8, v76, v55
	v_exp_f32_e32 v8, v8
	s_nop 0
	v_add_f32_e32 v9, v8, v9
	s_waitcnt vmcnt(1)
	v_pk_fma_f32 v[4:5], v[30:31], v[8:9], v[4:5] op_sel_hi:[1,0,1]
	v_pk_fma_f32 v[6:7], v[28:29], v[8:9], v[6:7] op_sel_hi:[1,0,1]
	v_sub_f32_e32 v8, v69, v55
	v_exp_f32_e32 v8, v8
	s_nop 0
	v_add_f32_e32 v9, v8, v9
	v_pk_fma_f32 v[6:7], v[24:25], v[8:9], v[6:7] op_sel_hi:[1,0,1]
	v_pk_fma_f32 v[4:5], v[26:27], v[8:9], v[4:5] op_sel_hi:[1,0,1]
	v_sub_f32_e32 v8, v68, v55
	v_exp_f32_e32 v8, v8
	s_nop 0
	v_add_f32_e32 v9, v8, v9
	v_pk_fma_f32 v[4:5], v[22:23], v[8:9], v[4:5] op_sel_hi:[1,0,1]
	v_pk_fma_f32 v[6:7], v[20:21], v[8:9], v[6:7] op_sel_hi:[1,0,1]
	v_sub_f32_e32 v8, v66, v55
	v_exp_f32_e32 v8, v8
	s_nop 0
	v_add_f32_e32 v9, v8, v9
	v_pk_fma_f32 v[6:7], v[16:17], v[8:9], v[6:7] op_sel_hi:[1,0,1]
	v_pk_fma_f32 v[4:5], v[18:19], v[8:9], v[4:5] op_sel_hi:[1,0,1]
	v_sub_f32_e32 v8, v64, v55
	v_exp_f32_e32 v8, v8
	s_nop 0
	v_add_f32_e32 v64, v8, v9
	s_waitcnt vmcnt(0)
	v_pk_fma_f32 v[68:69], v[14:15], v[8:9], v[4:5] op_sel_hi:[1,0,1]
	v_pk_fma_f32 v[90:91], v[12:13], v[8:9], v[6:7] op_sel_hi:[1,0,1]
	v_add_co_u32_e32 v4, vcc, s56, v48
	s_nop 1
	v_addc_co_u32_e32 v5, vcc, 0, v49, vcc
	v_add_co_u32_e32 v6, vcc, s93, v48
	s_nop 1
	v_addc_co_u32_e32 v7, vcc, 0, v49, vcc
	global_load_dwordx4 v[28:31], v[50:51], off offset:2048
	global_load_dwordx4 v[32:35], v[6:7], off offset:-4096
	global_load_dwordx4 v[36:39], v[6:7], off
	global_load_dwordx4 v[40:43], v[6:7], off offset:2048
	v_add_co_u32_e32 v6, vcc, s57, v48
	s_nop 1
	v_addc_co_u32_e32 v7, vcc, 0, v49, vcc
	v_add_co_u32_e32 v8, vcc, s6, v48
	s_nop 1
	v_addc_co_u32_e32 v9, vcc, 0, v49, vcc
	global_load_dwordx4 v[44:47], v[4:5], off offset:2048
	global_load_dwordx4 v[74:77], v[6:7], off offset:2048
	global_load_dwordx4 v[78:81], v[8:9], off offset:-4096
	global_load_dwordx4 v[82:85], v[8:9], off
	v_add_co_u32_e32 v4, vcc, s58, v48
	s_nop 1
	v_addc_co_u32_e32 v5, vcc, 0, v49, vcc
	v_add_co_u32_e32 v6, vcc, s95, v48
	s_nop 1
	v_addc_co_u32_e32 v7, vcc, 0, v49, vcc
	global_load_dwordx4 v[86:89], v[8:9], off offset:2048
	global_load_dwordx4 v[24:27], v[6:7], off offset:-4096
	global_load_dwordx4 v[16:19], v[6:7], off
	global_load_dwordx4 v[12:15], v[6:7], off offset:2048
	v_add_co_u32_e32 v6, vcc, s52, v48
	s_nop 1
	v_addc_co_u32_e32 v7, vcc, 0, v49, vcc
	global_load_dwordx4 v[20:23], v[4:5], off offset:2048
	global_load_dwordx4 v[8:11], v[6:7], off
	s_nop 0
	global_load_dwordx4 v[48:51], v[50:51], off
	s_nop 0
	global_load_dwordx4 v[4:7], v[6:7], off offset:2048
	v_sub_f32_e32 v62, v62, v55
	v_exp_f32_e32 v62, v62
	v_sub_f32_e32 v58, v58, v55
	v_exp_f32_e32 v58, v58
	s_waitcnt vmcnt(1)
	v_pk_fma_f32 v[48:49], v[48:49], v[62:63], v[90:91] op_sel_hi:[1,0,1]
	v_add_f32_e32 v64, v62, v64
	v_pk_fma_f32 v[28:29], v[28:29], v[58:59], v[48:49] op_sel_hi:[1,0,1]
	v_sub_f32_e32 v48, v61, v55
	v_exp_f32_e32 v48, v48
	v_pk_fma_f32 v[50:51], v[50:51], v[62:63], v[68:69] op_sel_hi:[1,0,1]
	v_add_f32_e32 v62, v58, v64
	v_pk_fma_f32 v[30:31], v[30:31], v[58:59], v[50:51] op_sel_hi:[1,0,1]
	v_add_f32_e32 v49, v48, v62
	v_pk_fma_f32 v[28:29], v[32:33], v[48:49], v[28:29] op_sel_hi:[1,0,1]
	v_sub_f32_e32 v32, v57, v55
	v_exp_f32_e32 v32, v32
	v_pk_fma_f32 v[30:31], v[34:35], v[48:49], v[30:31] op_sel_hi:[1,0,1]
	v_add_f32_e32 v33, v32, v49
	v_pk_fma_f32 v[30:31], v[46:47], v[32:33], v[30:31] op_sel_hi:[1,0,1]
	v_pk_fma_f32 v[28:29], v[44:45], v[32:33], v[28:29] op_sel_hi:[1,0,1]
	v_sub_f32_e32 v32, v60, v55
	v_exp_f32_e32 v32, v32
	s_nop 0
	v_add_f32_e32 v33, v32, v33
	v_pk_fma_f32 v[28:29], v[36:37], v[32:33], v[28:29] op_sel_hi:[1,0,1]
	v_pk_fma_f32 v[30:31], v[38:39], v[32:33], v[30:31] op_sel_hi:[1,0,1]
	v_sub_f32_e32 v32, v56, v55
	v_exp_f32_e32 v32, v32
	s_nop 0
	v_add_f32_e32 v33, v32, v33
	v_pk_fma_f32 v[30:31], v[42:43], v[32:33], v[30:31] op_sel_hi:[1,0,1]
	v_pk_fma_f32 v[28:29], v[40:41], v[32:33], v[28:29] op_sel_hi:[1,0,1]
	v_sub_f32_e32 v32, v63, v55
	v_exp_f32_e32 v32, v32
	s_nop 0
	v_add_f32_e32 v33, v32, v33
	v_pk_fma_f32 v[28:29], v[78:79], v[32:33], v[28:29] op_sel_hi:[1,0,1]
	v_pk_fma_f32 v[30:31], v[80:81], v[32:33], v[30:31] op_sel_hi:[1,0,1]
	v_sub_f32_e32 v32, v59, v55
	v_exp_f32_e32 v32, v32
	s_nop 0
	v_add_f32_e32 v33, v32, v33
	v_pk_fma_f32 v[30:31], v[76:77], v[32:33], v[30:31] op_sel_hi:[1,0,1]
	v_pk_fma_f32 v[28:29], v[74:75], v[32:33], v[28:29] op_sel_hi:[1,0,1]
	v_sub_f32_e32 v32, v54, v55
	v_exp_f32_e32 v32, v32
	s_nop 0
	v_add_f32_e32 v33, v32, v33
	v_pk_fma_f32 v[28:29], v[82:83], v[32:33], v[28:29] op_sel_hi:[1,0,1]
	v_pk_fma_f32 v[30:31], v[84:85], v[32:33], v[30:31] op_sel_hi:[1,0,1]
	v_sub_f32_e32 v32, v52, v55
	v_exp_f32_e32 v32, v32
	s_nop 0
	v_add_f32_e32 v33, v32, v33
	v_pk_fma_f32 v[30:31], v[88:89], v[32:33], v[30:31] op_sel_hi:[1,0,1]
	v_pk_fma_f32 v[28:29], v[86:87], v[32:33], v[28:29] op_sel_hi:[1,0,1]
	v_sub_f32_e32 v32, v73, v55
	v_exp_f32_e32 v32, v32
	s_nop 0
	v_add_f32_e32 v33, v32, v33
	v_pk_fma_f32 v[24:25], v[24:25], v[32:33], v[28:29] op_sel_hi:[1,0,1]
	v_sub_f32_e32 v28, v72, v55
	v_exp_f32_e32 v28, v28
	v_pk_fma_f32 v[26:27], v[26:27], v[32:33], v[30:31] op_sel_hi:[1,0,1]
	v_add_f32_e32 v29, v28, v33
	v_pk_fma_f32 v[20:21], v[20:21], v[28:29], v[24:25] op_sel_hi:[1,0,1]
	v_sub_f32_e32 v24, v70, v55
	v_exp_f32_e32 v24, v24
	v_pk_fma_f32 v[22:23], v[22:23], v[28:29], v[26:27] op_sel_hi:[1,0,1]
	v_add_f32_e32 v25, v24, v29
	v_pk_fma_f32 v[16:17], v[16:17], v[24:25], v[20:21] op_sel_hi:[1,0,1]
	v_sub_f32_e32 v20, v71, v55
	v_exp_f32_e32 v20, v20
	v_pk_fma_f32 v[18:19], v[18:19], v[24:25], v[22:23] op_sel_hi:[1,0,1]
	v_add_f32_e32 v21, v20, v25
	v_pk_fma_f32 v[12:13], v[12:13], v[20:21], v[16:17] op_sel_hi:[1,0,1]
	v_sub_f32_e32 v16, v67, v55
	v_exp_f32_e32 v16, v16
	v_pk_fma_f32 v[14:15], v[14:15], v[20:21], v[18:19] op_sel_hi:[1,0,1]
	v_add_f32_e32 v17, v16, v21
	v_pk_fma_f32 v[8:9], v[8:9], v[16:17], v[12:13] op_sel_hi:[1,0,1]
	v_sub_f32_e32 v12, v65, v55
	v_exp_f32_e32 v12, v12
	v_pk_fma_f32 v[10:11], v[10:11], v[16:17], v[14:15] op_sel_hi:[1,0,1]
	v_add_f32_e32 v13, v12, v17
	s_waitcnt vmcnt(0)
	v_pk_fma_f32 v[10:11], v[6:7], v[12:13], v[10:11] op_sel_hi:[1,0,1]
	v_pk_fma_f32 v[4:5], v[4:5], v[12:13], v[8:9] op_sel_hi:[1,0,1]
	ds_bpermute_b32 v12, v118, v13
	ds_bpermute_b32 v6, v118, v4
	ds_bpermute_b32 v7, v118, v5
	ds_bpermute_b32 v8, v118, v10
	ds_bpermute_b32 v9, v118, v11
	s_waitcnt lgkmcnt(4)
	v_add_f32_e32 v12, v13, v12
	ds_bpermute_b32 v13, v119, v12
	s_waitcnt lgkmcnt(3)
	v_pk_add_f32 v[4:5], v[4:5], v[6:7]
	ds_bpermute_b32 v6, v119, v4
	s_waitcnt lgkmcnt(2)
	v_pk_add_f32 v[8:9], v[10:11], v[8:9]
	ds_bpermute_b32 v7, v119, v5
	ds_bpermute_b32 v10, v119, v8
	ds_bpermute_b32 v11, v119, v9
	s_and_saveexec_b64 s[30:31], s[38:39]
	s_cbranch_execz .LBB0_630
	global_load_dwordx2 v[14:15], v2, s[22:23] offset:2048
	s_waitcnt lgkmcnt(2)
	v_pk_add_f32 v[4:5], v[4:5], v[6:7]
	s_waitcnt lgkmcnt(0)
	v_pk_add_f32 v[6:7], v[8:9], v[10:11]
	v_sub_f32_e32 v8, v53, v55
	v_sub_f32_e32 v9, v120, v55
	v_exp_f32_e32 v8, v8
	v_exp_f32_e32 v9, v9
	v_add_f32_e32 v12, v12, v13
	v_lshlrev_b32_e32 v18, 16, v107
	v_and_b32_e32 v19, 0xffff0000, v107
	v_add_f32_e32 v10, v8, v12
	v_pk_fma_f32 v[6:7], v[8:9], v[18:19], v[6:7] op_sel_hi:[0,1,1]
	v_add_f32_e32 v9, v9, v10
	s_mul_hi_i32 s1, s20, 0xc00
	s_mul_i32 s4, s20, 0xc00
	v_div_scale_f32 v10, s[20:21], v9, v9, 1.0
	v_rcp_f32_e32 v11, v10
	v_lshlrev_b32_e32 v16, 16, v106
	v_and_b32_e32 v17, 0xffff0000, v106
	v_pk_fma_f32 v[4:5], v[8:9], v[16:17], v[4:5] op_sel_hi:[0,1,1]
	v_fma_f32 v12, -v10, v11, 1.0
	v_div_scale_f32 v8, vcc, 1.0, v9, 1.0
	v_fmac_f32_e32 v11, v12, v11
	v_mul_f32_e32 v12, v8, v11
	v_fma_f32 v13, -v10, v12, v8
	v_fmac_f32_e32 v12, v13, v11
	v_fma_f32 v8, -v10, v12, v8
	s_lshl_b32 s0, s0, 6
	v_div_fmas_f32 v8, v8, v11, v12
	s_add_u32 s4, s81, s4
	v_div_fixup_f32 v8, v8, v9, 1.0
	s_addc_u32 s1, s9, s1
	s_lshl_b32 s0, s0, 1
	v_mul_f32_e32 v4, v8, v4
	v_mul_f32_e32 v5, v8, v5
	v_mul_f32_e32 v6, v8, v6
	v_mul_f32_e32 v7, v8, v7
	s_add_u32 s0, s4, s0
	s_addc_u32 s1, s1, 0
	s_waitcnt vmcnt(0)
	v_lshlrev_b32_e32 v8, 16, v14
	v_and_b32_e32 v9, 0xffff0000, v14
	v_lshlrev_b32_e32 v10, 16, v15
	v_and_b32_e32 v11, 0xffff0000, v15
	v_mul_f32_e32 v4, v4, v8
	v_mul_f32_e32 v5, v5, v9
	v_mul_f32_e32 v6, v6, v10
	v_mul_f32_e32 v7, v7, v11
	v_cvt_pk_bf16_f32 v4, v4, v5
	v_cvt_pk_bf16_f32 v5, v6, v7
	global_store_dwordx2 v2, v[4:5], s[0:1] sc1
	s_branch .LBB0_630

.Lmy_sc_la:
	s_or_b64 exec, exec, s[42:43]
	v_lshl_add_u64 v[136:137], s[52:53], 0, v[80:81]
	s_waitcnt lgkmcnt(0)
	v_lshl_add_u64 v[4:5], v[136:137], 2, s[44:45]
	v_and_b32_e32 v139, 63, v132
	v_lshl_add_u64 v[4:5], v[4:5], 0, v[2:3]
	v_add_co_u32_e32 v6, vcc, 0x1000, v4
	s_nop 1
	v_addc_co_u32_e32 v7, vcc, 0, v5, vcc
	global_load_dwordx4 v[80:83], v[4:5], off nt
	global_load_dwordx4 v[76:79], v[6:7], off nt
	v_add_co_u32_e32 v6, vcc, s63, v4
	s_nop 1
	v_addc_co_u32_e32 v7, vcc, 0, v5, vcc
	v_add_co_u32_e32 v8, vcc, 0x3000, v4
	s_nop 1
	v_addc_co_u32_e32 v9, vcc, 0, v5, vcc
	global_load_dwordx4 v[68:71], v[6:7], off nt
	global_load_dwordx4 v[60:63], v[8:9], off nt
	v_add_co_u32_e32 v6, vcc, s14, v4
	s_nop 1
	v_addc_co_u32_e32 v7, vcc, 0, v5, vcc
	v_add_co_u32_e32 v8, vcc, 0x5000, v4
	s_nop 1
	v_addc_co_u32_e32 v9, vcc, 0, v5, vcc
	global_load_dwordx4 v[56:59], v[6:7], off nt
	global_load_dwordx4 v[48:51], v[8:9], off nt
	v_add_co_u32_e32 v6, vcc, s33, v4
	s_nop 1
	v_addc_co_u32_e32 v7, vcc, 0, v5, vcc
	v_add_co_u32_e32 v8, vcc, 0x7000, v4
	s_nop 1
	v_addc_co_u32_e32 v9, vcc, 0, v5, vcc
	global_load_dwordx4 v[44:47], v[6:7], off nt
	global_load_dwordx4 v[36:39], v[8:9], off nt
	v_add_co_u32_e32 v6, vcc, s24, v4
	s_nop 1
	v_addc_co_u32_e32 v7, vcc, 0, v5, vcc
	v_add_co_u32_e32 v8, vcc, 0x9000, v4
	s_nop 1
	v_addc_co_u32_e32 v9, vcc, 0, v5, vcc
	global_load_dwordx4 v[32:35], v[6:7], off nt
	global_load_dwordx4 v[28:31], v[8:9], off nt
	v_add_co_u32_e32 v6, vcc, s20, v4
	s_nop 1
	v_addc_co_u32_e32 v7, vcc, 0, v5, vcc
	v_add_co_u32_e32 v8, vcc, 0xb000, v4
	s_nop 1
	v_addc_co_u32_e32 v9, vcc, 0, v5, vcc
	global_load_dwordx4 v[24:27], v[6:7], off nt
	global_load_dwordx4 v[20:23], v[8:9], off nt
	v_add_co_u32_e32 v6, vcc, s6, v4
	s_nop 1
	v_addc_co_u32_e32 v7, vcc, 0, v5, vcc
	v_add_co_u32_e32 v8, vcc, 0xd000, v4
	s_nop 1
	v_addc_co_u32_e32 v9, vcc, 0, v5, vcc
	global_load_dwordx4 v[16:19], v[6:7], off nt
	global_load_dwordx4 v[12:15], v[8:9], off nt
	v_add_co_u32_e32 v6, vcc, s30, v4
	s_nop 1
	v_addc_co_u32_e32 v7, vcc, 0, v5, vcc
	v_add_co_u32_e32 v4, vcc, 0xf000, v4
	s_nop 1
	v_addc_co_u32_e32 v5, vcc, 0, v5, vcc
	global_load_dwordx4 v[8:11], v[6:7], off nt
	s_nop 0
	global_load_dwordx4 v[4:7], v[4:5], off nt
	v_lshl_add_u32 v140, v139, 2, 0
	s_barrier
	ds_read2st64_b32 v[142:143], v140 offset1:1
	ds_read2st64_b32 v[144:145], v140 offset0:2 offset1:3
	s_waitcnt lgkmcnt(0)
	v_max_f32_e32 v141, v145, v145
	v_max_f32_e32 v146, v144, v144
	v_max_f32_e32 v141, v146, v141
	v_max3_f32 v141, v142, v143, v141
	s_nop 1
	v_max_f32_dpp v141, v141, v141 quad_perm:[1,0,3,2] row_mask:0xf bank_mask:0xf
	s_nop 1
	v_max_f32_dpp v141, v141, v141 quad_perm:[2,3,0,1] row_mask:0xf bank_mask:0xf
	s_nop 1
	v_max_f32_dpp v141, v141, v141 row_half_mirror row_mask:0xf bank_mask:0xf
	s_nop 1
	v_max_f32_dpp v141, v141, v141 row_mirror row_mask:0xf bank_mask:0xf
	s_nop 1
	ds_bpermute_b32 v146, v209, v141
	s_waitcnt lgkmcnt(0)
	v_max_f32_e32 v146, v146, v146
	v_max_f32_e32 v141, v141, v146
	ds_bpermute_b32 v146, v197, v141
	s_waitcnt lgkmcnt(0)
	v_max_f32_e32 v146, v146, v146
	v_max_f32_e32 v141, v141, v146
	v_sub_f32_e32 v143, v143, v141
	v_sub_f32_e32 v142, v142, v141
	v_exp_f32_e32 v146, v143
	v_sub_f32_e32 v143, v144, v141
	v_sub_f32_e32 v144, v145, v141
	v_exp_f32_e32 v142, v142
	v_exp_f32_e32 v143, v143
	v_exp_f32_e32 v147, v144
	s_nop 0
	v_pk_add_f32 v[142:143], v[142:143], v[146:147]
	s_nop 0
	v_add_f32_e32 v142, v142, v143
	s_nop 1
	v_add_f32_dpp v142, v142, v142 quad_perm:[1,0,3,2] row_mask:0xf bank_mask:0xf
	s_nop 1
	v_add_f32_dpp v142, v142, v142 quad_perm:[2,3,0,1] row_mask:0xf bank_mask:0xf
	s_nop 1
	v_add_f32_dpp v142, v142, v142 row_half_mirror row_mask:0xf bank_mask:0xf
	s_nop 1
	v_add_f32_dpp v142, v142, v142 row_mirror row_mask:0xf bank_mask:0xf
	s_nop 1
	ds_bpermute_b32 v143, v209, v142
	s_waitcnt lgkmcnt(0)
	v_add_f32_e32 v142, v142, v143
	ds_bpermute_b32 v143, v197, v142
	s_waitcnt lgkmcnt(0)
	v_add_f32_e32 v142, v142, v143
	v_div_scale_f32 v143, s[42:43], v142, v142, 1.0
	v_rcp_f32_e32 v144, v143
	v_cmp_gt_u32_e64 s[42:43], 32, v139
	v_lshl_add_u32 v139, v133, 4, s91
	v_fma_f32 v145, -v143, v144, 1.0
	v_fmac_f32_e32 v144, v145, v144
	v_div_scale_f32 v145, vcc, 1.0, v142, 1.0
	v_mul_f32_e32 v146, v145, v144
	v_fma_f32 v147, -v143, v146, v145
	v_fmac_f32_e32 v146, v147, v144
	v_fma_f32 v143, -v143, v146, v145
	v_div_fmas_f32 v143, v143, v144, v146
	ds_read2_b32 v[144:145], v138 offset1:2
	ds_read2_b32 v[146:147], v138 offset0:4 offset1:6
	ds_read2_b32 v[148:149], v138 offset0:8 offset1:10
	ds_read2_b32 v[150:151], v138 offset0:12 offset1:14
	v_div_fixup_f32 v142, v143, v142, 1.0
	s_waitcnt lgkmcnt(3)
	v_sub_f32_e32 v143, v144, v141
	v_exp_f32_e32 v143, v143
	s_nop 0
	v_mul_f32_e32 v144, v143, v142
	v_sub_f32_e32 v143, v145, v141
	v_exp_f32_e32 v143, v143
	s_waitcnt vmcnt(17)
	v_pk_fma_f32 v[128:129], v[128:129], v[144:145], 0 op_sel_hi:[1,0,0]
	v_pk_fma_f32 v[130:131], v[130:131], v[144:145], 0 op_sel_hi:[1,0,0]
	v_mul_f32_e32 v144, v143, v142
	v_pk_fma_f32 v[124:125], v[124:125], v[144:145], v[128:129] op_sel_hi:[1,0,1]
	s_waitcnt lgkmcnt(2)
	v_sub_f32_e32 v128, v146, v141
	v_exp_f32_e32 v128, v128
	v_pk_fma_f32 v[126:127], v[126:127], v[144:145], v[130:131] op_sel_hi:[1,0,1]
	v_mul_f32_e32 v128, v128, v142
	v_pk_fma_f32 v[116:117], v[116:117], v[128:129], v[124:125] op_sel_hi:[1,0,1]
	v_sub_f32_e32 v124, v147, v141
	v_exp_f32_e32 v124, v124
	v_pk_fma_f32 v[118:119], v[118:119], v[128:129], v[126:127] op_sel_hi:[1,0,1]
	v_mul_f32_e32 v124, v124, v142
	v_pk_fma_f32 v[116:117], v[120:121], v[124:125], v[116:117] op_sel_hi:[1,0,1]
	s_waitcnt lgkmcnt(1)
	v_sub_f32_e32 v120, v148, v141
	v_exp_f32_e32 v120, v120
	v_pk_fma_f32 v[118:119], v[122:123], v[124:125], v[118:119] op_sel_hi:[1,0,1]
	v_mul_f32_e32 v120, v142, v120
	v_pk_fma_f32 v[108:109], v[108:109], v[120:121], v[116:117] op_sel_hi:[1,0,1]
	v_sub_f32_e32 v116, v149, v141
	v_exp_f32_e32 v116, v116
	v_pk_fma_f32 v[110:111], v[110:111], v[120:121], v[118:119] op_sel_hi:[1,0,1]
	v_mul_f32_e32 v116, v142, v116
	v_pk_fma_f32 v[108:109], v[112:113], v[116:117], v[108:109] op_sel_hi:[1,0,1]
	s_waitcnt lgkmcnt(0)
	v_sub_f32_e32 v112, v150, v141
	v_exp_f32_e32 v112, v112
	v_pk_fma_f32 v[110:111], v[114:115], v[116:117], v[110:111] op_sel_hi:[1,0,1]
	v_mul_f32_e32 v112, v142, v112
	v_pk_fma_f32 v[100:101], v[100:101], v[112:113], v[108:109] op_sel_hi:[1,0,1]
	v_sub_f32_e32 v108, v151, v141
	v_exp_f32_e32 v108, v108
	v_pk_fma_f32 v[102:103], v[102:103], v[112:113], v[110:111] op_sel_hi:[1,0,1]
	v_mul_f32_e32 v108, v142, v108
	v_pk_fma_f32 v[100:101], v[104:105], v[108:109], v[100:101] op_sel_hi:[1,0,1]
	ds_read2_b32 v[104:105], v138 offset0:16 offset1:18
	v_pk_fma_f32 v[102:103], v[106:107], v[108:109], v[102:103] op_sel_hi:[1,0,1]
	s_waitcnt lgkmcnt(0)
	v_sub_f32_e32 v104, v104, v141
	v_exp_f32_e32 v104, v104
	s_nop 0
	v_mul_f32_e32 v104, v142, v104
	v_pk_fma_f32 v[100:101], v[92:93], v[104:105], v[100:101] op_sel_hi:[1,0,1]
	v_pk_fma_f32 v[92:93], v[94:95], v[104:105], v[102:103] op_sel_hi:[1,0,1]
	v_sub_f32_e32 v94, v105, v141
	v_exp_f32_e32 v94, v94
	s_nop 0
	v_mul_f32_e32 v94, v142, v94
	v_pk_fma_f32 v[92:93], v[98:99], v[94:95], v[92:93] op_sel_hi:[1,0,1]
	v_pk_fma_f32 v[94:95], v[96:97], v[94:95], v[100:101] op_sel_hi:[1,0,1]
	ds_read2_b32 v[96:97], v138 offset0:20 offset1:22
	s_waitcnt lgkmcnt(0)
	v_sub_f32_e32 v96, v96, v141
	v_exp_f32_e32 v96, v96
	s_nop 0
	v_mul_f32_e32 v96, v142, v96
	v_pk_fma_f32 v[86:87], v[86:87], v[96:97], v[92:93] op_sel_hi:[1,0,1]
	v_sub_f32_e32 v92, v97, v141
	v_exp_f32_e32 v92, v92
	v_pk_fma_f32 v[84:85], v[84:85], v[96:97], v[94:95] op_sel_hi:[1,0,1]
	v_mul_f32_e32 v92, v142, v92
	v_pk_fma_f32 v[84:85], v[88:89], v[92:93], v[84:85] op_sel_hi:[1,0,1]
	ds_read2_b32 v[88:89], v138 offset0:24 offset1:26
	v_pk_fma_f32 v[86:87], v[90:91], v[92:93], v[86:87] op_sel_hi:[1,0,1]
	s_waitcnt lgkmcnt(0)
	v_sub_f32_e32 v88, v88, v141
	v_exp_f32_e32 v88, v88
	s_nop 0
	v_mul_f32_e32 v88, v142, v88
	v_pk_fma_f32 v[72:73], v[72:73], v[88:89], v[84:85] op_sel_hi:[1,0,1]
	v_sub_f32_e32 v84, v89, v141
	v_exp_f32_e32 v84, v84
	v_pk_fma_f32 v[74:75], v[74:75], v[88:89], v[86:87] op_sel_hi:[1,0,1]
	v_mul_f32_e32 v84, v142, v84
	v_pk_fma_f32 v[64:65], v[64:65], v[84:85], v[72:73] op_sel_hi:[1,0,1]
	ds_read2_b32 v[72:73], v138 offset0:28 offset1:30
	v_pk_fma_f32 v[66:67], v[66:67], v[84:85], v[74:75] op_sel_hi:[1,0,1]
	s_waitcnt lgkmcnt(0)
	v_sub_f32_e32 v72, v72, v141
	v_exp_f32_e32 v72, v72
	s_nop 0
	v_mul_f32_e32 v72, v142, v72
	v_pk_fma_f32 v[64:65], v[52:53], v[72:73], v[64:65] op_sel_hi:[1,0,1]
	v_pk_fma_f32 v[52:53], v[54:55], v[72:73], v[66:67] op_sel_hi:[1,0,1]
	v_sub_f32_e32 v54, v73, v141
	v_exp_f32_e32 v54, v54
	s_nop 0
	v_mul_f32_e32 v54, v142, v54
	s_waitcnt vmcnt(16)
	v_pk_fma_f32 v[52:53], v[42:43], v[54:55], v[52:53] op_sel_hi:[1,0,1]
	v_pk_fma_f32 v[40:41], v[40:41], v[54:55], v[64:65] op_sel_hi:[1,0,1]
	ds_bpermute_b32 v42, v197, v40
	ds_bpermute_b32 v43, v197, v41
	ds_bpermute_b32 v54, v197, v52
	ds_bpermute_b32 v55, v197, v53
	s_and_saveexec_b64 s[44:45], s[42:43]
	s_cbranch_execz .LBB0_717
	s_waitcnt lgkmcnt(0)
	v_pk_add_f32 v[54:55], v[52:53], v[54:55]
	v_pk_add_f32 v[52:53], v[40:41], v[42:43]
	ds_write_b128 v139, v[52:55] offset:2048

.Lmy_sc_lb:
	s_or_b64 exec, exec, s[46:47]
	s_waitcnt lgkmcnt(0)
	s_barrier
	ds_read2st64_b32 v[4:5], v140 offset0:4 offset1:5
	ds_read2st64_b32 v[6:7], v140 offset0:6 offset1:7
	v_add_u32_e32 v12, 0x400, v138
	s_waitcnt lgkmcnt(0)
	v_max_f32_e32 v8, v7, v7
	v_max_f32_e32 v9, v6, v6
	v_max_f32_e32 v8, v9, v8
	v_max3_f32 v8, v4, v5, v8
	s_nop 1
	v_max_f32_dpp v8, v8, v8 quad_perm:[1,0,3,2] row_mask:0xf bank_mask:0xf
	s_nop 1
	v_max_f32_dpp v8, v8, v8 quad_perm:[2,3,0,1] row_mask:0xf bank_mask:0xf
	s_nop 1
	v_max_f32_dpp v8, v8, v8 row_half_mirror row_mask:0xf bank_mask:0xf
	s_nop 1
	v_max_f32_dpp v8, v8, v8 row_mirror row_mask:0xf bank_mask:0xf
	s_nop 1
	ds_bpermute_b32 v9, v209, v8
	s_waitcnt lgkmcnt(0)
	v_max_f32_e32 v9, v9, v9
	v_max_f32_e32 v8, v8, v9
	ds_bpermute_b32 v9, v197, v8
	s_waitcnt lgkmcnt(0)
	v_max_f32_e32 v9, v9, v9
	v_max_f32_e32 v10, v8, v9
	v_sub_f32_e32 v5, v5, v10
	v_sub_f32_e32 v4, v4, v10
	v_exp_f32_e32 v8, v5
	v_sub_f32_e32 v5, v6, v10
	v_sub_f32_e32 v6, v7, v10
	v_exp_f32_e32 v4, v4
	v_exp_f32_e32 v5, v5
	v_exp_f32_e32 v9, v6
	s_nop 0
	v_pk_add_f32 v[4:5], v[4:5], v[8:9]
	s_nop 0
	v_add_f32_e32 v4, v4, v5
	s_nop 1
	v_add_f32_dpp v4, v4, v4 quad_perm:[1,0,3,2] row_mask:0xf bank_mask:0xf
	s_nop 1
	v_add_f32_dpp v4, v4, v4 quad_perm:[2,3,0,1] row_mask:0xf bank_mask:0xf
	s_nop 1
	v_add_f32_dpp v4, v4, v4 row_half_mirror row_mask:0xf bank_mask:0xf
	s_nop 1
	v_add_f32_dpp v4, v4, v4 row_mirror row_mask:0xf bank_mask:0xf
	s_nop 1
	ds_bpermute_b32 v5, v209, v4
	s_waitcnt lgkmcnt(0)
	v_add_f32_e32 v4, v4, v5
	ds_bpermute_b32 v5, v197, v4
	s_waitcnt lgkmcnt(0)
	v_add_f32_e32 v4, v4, v5
	v_div_scale_f32 v5, s[40:41], v4, v4, 1.0
	v_rcp_f32_e32 v6, v5
	s_nop 0
	v_fma_f32 v7, -v5, v6, 1.0
	v_fmac_f32_e32 v6, v7, v6
	v_div_scale_f32 v7, vcc, 1.0, v4, 1.0
	v_mul_f32_e32 v8, v7, v6
	v_fma_f32 v9, -v5, v8, v7
	v_fmac_f32_e32 v8, v9, v6
	v_fma_f32 v5, -v5, v8, v7
	v_div_fmas_f32 v5, v5, v6, v8
	v_div_fixup_f32 v11, v5, v4, 1.0
	ds_read2_b32 v[4:5], v12 offset1:2
	ds_read2_b32 v[6:7], v12 offset0:4 offset1:6
	ds_read2_b32 v[8:9], v12 offset0:8 offset1:10
	ds_read2_b32 v[14:15], v12 offset0:12 offset1:14
	s_waitcnt lgkmcnt(3)
	v_sub_f32_e32 v4, v4, v10
	v_exp_f32_e32 v4, v4
	s_waitcnt lgkmcnt(2)
	v_sub_f32_e32 v6, v6, v10
	v_exp_f32_e32 v6, v6
	v_mul_f32_e32 v4, v4, v11
	s_waitcnt vmcnt(15)
	v_pk_fma_f32 v[16:17], v[104:105], v[4:5], 0 op_sel_hi:[1,0,0]
	v_pk_fma_f32 v[18:19], v[106:107], v[4:5], 0 op_sel_hi:[1,0,0]
	v_sub_f32_e32 v4, v5, v10
	v_exp_f32_e32 v4, v4
	v_mul_f32_e32 v6, v6, v11
	v_mul_f32_e32 v4, v4, v11
	s_waitcnt vmcnt(14)
	v_pk_fma_f32 v[18:19], v[102:103], v[4:5], v[18:19] op_sel_hi:[1,0,1]
	v_pk_fma_f32 v[4:5], v[100:101], v[4:5], v[16:17] op_sel_hi:[1,0,1]
	s_waitcnt vmcnt(13)
	v_pk_fma_f32 v[16:17], v[114:115], v[6:7], v[18:19] op_sel_hi:[1,0,1]
	v_pk_fma_f32 v[4:5], v[112:113], v[6:7], v[4:5] op_sel_hi:[1,0,1]
	v_sub_f32_e32 v6, v7, v10
	v_exp_f32_e32 v6, v6
	s_nop 0
	v_mul_f32_e32 v6, v6, v11
	s_waitcnt vmcnt(12)
	v_pk_fma_f32 v[16:17], v[110:111], v[6:7], v[16:17] op_sel_hi:[1,0,1]
	v_pk_fma_f32 v[4:5], v[108:109], v[6:7], v[4:5] op_sel_hi:[1,0,1]
	s_waitcnt lgkmcnt(1)
	v_sub_f32_e32 v6, v8, v10
	v_exp_f32_e32 v6, v6
	v_sub_f32_e32 v8, v9, v10
	v_exp_f32_e32 v8, v8
	v_mul_f32_e32 v6, v11, v6
	s_waitcnt vmcnt(11)
	v_pk_fma_f32 v[4:5], v[120:121], v[6:7], v[4:5] op_sel_hi:[1,0,1]
	v_pk_fma_f32 v[6:7], v[122:123], v[6:7], v[16:17] op_sel_hi:[1,0,1]
	v_mul_f32_e32 v8, v11, v8
	s_waitcnt vmcnt(10)
	v_pk_fma_f32 v[6:7], v[118:119], v[8:9], v[6:7] op_sel_hi:[1,0,1]
	v_pk_fma_f32 v[4:5], v[116:117], v[8:9], v[4:5] op_sel_hi:[1,0,1]
	s_waitcnt lgkmcnt(0)
	v_sub_f32_e32 v8, v14, v10
	v_exp_f32_e32 v8, v8
	s_nop 0
	v_mul_f32_e32 v8, v11, v8
	s_waitcnt vmcnt(9)
	v_pk_fma_f32 v[4:5], v[128:129], v[8:9], v[4:5] op_sel_hi:[1,0,1]
	v_pk_fma_f32 v[6:7], v[130:131], v[8:9], v[6:7] op_sel_hi:[1,0,1]
	v_sub_f32_e32 v8, v15, v10
	v_exp_f32_e32 v8, v8
	s_nop 0
	v_mul_f32_e32 v8, v11, v8
	s_waitcnt vmcnt(8)
	v_pk_fma_f32 v[6:7], v[126:127], v[8:9], v[6:7] op_sel_hi:[1,0,1]
	v_pk_fma_f32 v[4:5], v[124:125], v[8:9], v[4:5] op_sel_hi:[1,0,1]
	ds_read2_b32 v[8:9], v12 offset0:16 offset1:18
	s_waitcnt lgkmcnt(0)
	v_sub_f32_e32 v8, v8, v10
	v_exp_f32_e32 v8, v8
	s_nop 0
	v_mul_f32_e32 v8, v11, v8
	s_waitcnt vmcnt(7)
	v_pk_fma_f32 v[14:15], v[96:97], v[8:9], v[4:5] op_sel_hi:[1,0,1]
	v_pk_fma_f32 v[4:5], v[98:99], v[8:9], v[6:7] op_sel_hi:[1,0,1]
	v_sub_f32_e32 v6, v9, v10
	ds_read2_b32 v[8:9], v12 offset0:20 offset1:22
	v_exp_f32_e32 v6, v6
	s_waitcnt lgkmcnt(0)
	v_sub_f32_e32 v8, v8, v10
	v_exp_f32_e32 v8, v8
	v_mul_f32_e32 v6, v11, v6
	s_waitcnt vmcnt(6)
	v_pk_fma_f32 v[4:5], v[94:95], v[6:7], v[4:5] op_sel_hi:[1,0,1]
	v_pk_fma_f32 v[6:7], v[92:93], v[6:7], v[14:15] op_sel_hi:[1,0,1]
	v_mul_f32_e32 v8, v11, v8
	s_waitcnt vmcnt(5)
	v_pk_fma_f32 v[6:7], v[88:89], v[8:9], v[6:7] op_sel_hi:[1,0,1]
	v_pk_fma_f32 v[4:5], v[90:91], v[8:9], v[4:5] op_sel_hi:[1,0,1]
	v_sub_f32_e32 v8, v9, v10
	v_exp_f32_e32 v8, v8
	s_nop 0
	v_mul_f32_e32 v8, v11, v8
	s_waitcnt vmcnt(4)
	v_pk_fma_f32 v[4:5], v[86:87], v[8:9], v[4:5] op_sel_hi:[1,0,1]
	v_pk_fma_f32 v[6:7], v[84:85], v[8:9], v[6:7] op_sel_hi:[1,0,1]
	ds_read2_b32 v[8:9], v12 offset0:24 offset1:26
	s_waitcnt lgkmcnt(0)
	v_sub_f32_e32 v8, v8, v10
	v_exp_f32_e32 v8, v8
	s_nop 0
	v_mul_f32_e32 v8, v11, v8
	s_waitcnt vmcnt(3)
	v_pk_fma_f32 v[6:7], v[72:73], v[8:9], v[6:7] op_sel_hi:[1,0,1]
	v_pk_fma_f32 v[4:5], v[74:75], v[8:9], v[4:5] op_sel_hi:[1,0,1]
	v_sub_f32_e32 v8, v9, v10
	v_exp_f32_e32 v8, v8
	s_nop 0
	v_mul_f32_e32 v8, v11, v8
	s_waitcnt vmcnt(2)
	v_pk_fma_f32 v[4:5], v[66:67], v[8:9], v[4:5] op_sel_hi:[1,0,1]
	v_pk_fma_f32 v[6:7], v[64:65], v[8:9], v[6:7] op_sel_hi:[1,0,1]
	ds_read2_b32 v[8:9], v12 offset0:28 offset1:30
	s_waitcnt lgkmcnt(0)
	v_sub_f32_e32 v8, v8, v10
	v_exp_f32_e32 v8, v8
	s_nop 0
	v_mul_f32_e32 v8, v11, v8
	s_waitcnt vmcnt(1)
	v_pk_fma_f32 v[6:7], v[52:53], v[8:9], v[6:7] op_sel_hi:[1,0,1]
	v_pk_fma_f32 v[4:5], v[54:55], v[8:9], v[4:5] op_sel_hi:[1,0,1]
	v_sub_f32_e32 v8, v9, v10
	v_exp_f32_e32 v8, v8
	s_nop 0
	v_mul_f32_e32 v10, v11, v8
	s_waitcnt vmcnt(0)
	v_pk_fma_f32 v[8:9], v[42:43], v[10:11], v[4:5] op_sel_hi:[1,0,1]
	v_pk_fma_f32 v[4:5], v[40:41], v[10:11], v[6:7] op_sel_hi:[1,0,1]
	ds_bpermute_b32 v6, v197, v4
	ds_bpermute_b32 v7, v197, v5
	ds_bpermute_b32 v10, v197, v8
	ds_bpermute_b32 v11, v197, v9
	s_and_saveexec_b64 s[40:41], s[42:43]
	s_cbranch_execz .LBB0_753
	s_waitcnt lgkmcnt(0)
	v_pk_add_f32 v[8:9], v[8:9], v[10:11]
	v_pk_add_f32 v[6:7], v[4:5], v[6:7]
	ds_write_b128 v139, v[6:9] offset:2048
